# v24 + odd-layer attention: 0.125*log2e folded into the prepared query before its bf16 rounding and the fixed softmax reference into the QK accumulator init (64 v_fmamk per step removed)
# speedup vs baseline: 1.0100x; 1.0100x over previous
; DI const float* in_ptr(const Args& AR, int i) { asm volatile("" : "+s"(i)); return GLOBAL_PTR(const float, AR.in[i]); }
; DI void attn_odd_lds(Frame& F, const float* gk  , const float* gq  , bool with_ctx) {
;     const bf16_t* P = WSP(bf16_t, WS_BIG); const bf16_t* VT = WSP(bf16_t, WS_VT); bf16_t* MIX = WSP(bf16_t, WS_H);
;     const int l16 = F.lane & 15, g = F.lane >> 4;
;     const size_t kp = LDP_O;
;     const unsigned lds0 = (unsigned)(uintptr_t)F.lds;
;     const int drow = F.wave * 8 + (F.lane & 7), dsw = (F.lane >> 3) * 8;
;     const unsigned koff = (unsigned)(drow * (int)kp + dsw) * 2u, voff = (unsigned)(drow * TT + dsw) * 2u;
;     const unsigned wofs = (unsigned)F.wave * AT_GRP;
;     const float kn = 8.0f * 1.01f * wave_max(fabsf(gk[F.lane])) * (0.125f * LOG2E);
;     const int bk = (l16 >> 3) * AT_GRP + (l16 & 7) * 16 + g * 128, bv = AT_VOFF + (l16 >> 3) * AT_GRP + (l16 & 7) * 16 + (g >> 1) * 128 + (g & 1) * 8;
;     __syncthreads();
; __global__ void __launch_bounds__(512, 2) fwd_megakernel(Args args) {
;     ...
;             } else if (type == T_ATTE) {
;                 if (PM & 1024) { const float* qg_ = in_ptr(AR, 11) + li * 128; attn_even_lds(F, in_ptr(AR, 12) + (size_t)li * 12 * 465, qg_ + 64, qg_); attn_evenctx_lds(F, qg_ + 64, qg_); }
;             } else if (type == T_ATTO) {
;                 if (PM & 2048) { const float* qg_ = in_ptr(AR, 15) + li * 128; attn_odd_lds(F, qg_ + 64, qg_, l < 3); }
.LBB0_233:
	s_add_u32 s58, s60, 0x10900000
	s_addc_u32 s59, s61, 0
	s_add_u32 s62, s60, 0x19100000
	s_addc_u32 s63, s61, 0
	s_ashr_i32 s50, s79, 6
	v_writelane_b32 v255, s12, 23
	v_and_b32_e32 v194, 63, v164
	s_cmp_lt_i32 s35, 5
	s_mov_b64 s[4:5], -1
	s_cbranch_scc1 .LBB0_441
	s_cmp_lt_i32 s35, 7
	s_cbranch_scc1 .LBB0_351
	s_cmp_lt_i32 s35, 8
	s_cbranch_scc1 .LBB0_341
	s_cmp_lt_i32 s35, 9
	s_cbranch_scc1 .LBB0_271
	s_cmp_eq_u32 s35, 9
	s_cbranch_scc0 .LBB0_270
	s_mov_b32 s4, 15
	s_ashr_i32 s5, s4, 31
	s_lshl_b64 s[4:5], s[4:5], 3
	s_add_u32 s4, s0, s4
	v_readlane_b32 s6, v255, 15
	s_addc_u32 s5, s1, s5
	v_readlane_b32 s7, v255, 16
	s_load_dwordx2 s[4:5], s[4:5], 0x0
	s_lshl_b64 s[6:7], s[6:7], 2
	s_waitcnt lgkmcnt(0)
	s_add_u32 s6, s4, s6
	s_addc_u32 s7, s5, s7
	v_lshlrev_b32_e32 v0, 2, v194
	global_load_dword v2, v0, s[6:7] offset:256
	v_cmp_lt_i32_e32 vcc, v181, v180
	v_readlane_b32 s4, v255, 27
	s_cmp_ge_i32 s26, s4
	v_cndmask_b32_e32 v4, v169, v181, vcc
	v_lshlrev_b32_e32 v4, 2, v4
	v_cmp_lt_i32_e32 vcc, v182, v180
	s_barrier
	s_waitcnt vmcnt(0)
	v_and_b32_e32 v3, 0x7fffffff, v2
	ds_bpermute_b32 v3, v4, v3
	v_max_f32_e64 v2, |v2|, |v2|
	s_waitcnt lgkmcnt(0)
	v_max_f32_e32 v3, v3, v3
	v_max_f32_e32 v2, v2, v3
	v_cndmask_b32_e32 v3, v169, v182, vcc
	v_lshlrev_b32_e32 v3, 2, v3
	ds_bpermute_b32 v3, v3, v2
	v_cmp_lt_i32_e32 vcc, v183, v180
	s_waitcnt lgkmcnt(0)
	v_max_f32_e32 v3, v3, v3
	v_max_f32_e32 v2, v2, v3
	v_cndmask_b32_e32 v3, v169, v183, vcc
	v_lshlrev_b32_e32 v3, 2, v3
	ds_bpermute_b32 v3, v3, v2
	v_cmp_lt_i32_e32 vcc, v192, v180
	s_waitcnt lgkmcnt(0)
	v_max_f32_e32 v3, v3, v3
	v_max_f32_e32 v2, v2, v3
	v_cndmask_b32_e32 v3, v169, v192, vcc
	v_lshlrev_b32_e32 v3, 2, v3
	ds_bpermute_b32 v3, v3, v2
	v_cmp_lt_i32_e32 vcc, v254, v180
	s_waitcnt lgkmcnt(0)
	v_max_f32_e32 v3, v3, v3
	v_max_f32_e32 v2, v2, v3
	v_cndmask_b32_e32 v3, v169, v254, vcc
	v_lshlrev_b32_e32 v120, 2, v3
	ds_bpermute_b32 v3, v120, v2
	v_cmp_lt_i32_e32 vcc, v186, v180
	s_waitcnt lgkmcnt(0)
	v_max_f32_e32 v3, v3, v3
	v_max_f32_e32 v2, v2, v3
	v_cndmask_b32_e32 v3, v169, v186, vcc
	v_lshlrev_b32_e32 v121, 2, v3
	ds_bpermute_b32 v3, v121, v2
	s_cbranch_scc1 .LBB0_270
	s_waitcnt lgkmcnt(0)
	v_max_f32_e32 v3, v3, v3
	v_max_f32_e32 v2, v2, v3
	v_and_b32_e32 v3, 7, v164
	v_lshl_or_b32 v3, s50, 3, v3
	s_movk_i32 s4, 0x700
	v_mul_lo_u32 v5, v3, s4
	s_mov_b32 s4, 0x11000
	s_add_u32 s42, s60, 0x2c300000
	v_and_b32_e32 v4, 56, v164
	v_mul_lo_u32 v3, v3, s4
	s_mul_i32 s4, s50, 0x480
	s_addc_u32 s43, s61, 0
	v_and_b32_e32 v122, 15, v164
	v_or_b32_e32 v3, v3, v4
	v_mul_f32_e32 v2, 0x410147ae, v2
	s_add_i32 s80, s4, 0
	s_lshl_b32 s83, s50, 4
	v_lshrrev_b32_e32 v123, 4, v194
	v_or_b32_e32 v5, v5, v4
	v_lshlrev_b32_e32 v125, 1, v3
	v_mov_b32_e32 v126, v2
	v_lshlrev_b32_e32 v2, 4, v194
	v_bfe_u32 v3, v164, 3, 1
	s_add_i32 s81, s80, 0x4800
	s_add_i32 s82, s80, 0x9000
	v_or_b32_e32 v4, s83, v122
	v_and_b32_e32 v2, 0x70, v2
	v_and_b32_e32 v128, 0x80, v0
	v_lshlrev_b32_e32 v0, 3, v123
	v_mul_u32_u24_e32 v3, 0x480, v3
	s_add_u32 s8, s60, 0x400000
	v_lshlrev_b32_e32 v4, 4, v4
	s_mov_b32 s84, s26
	v_lshlrev_b32_e32 v124, 1, v5
	v_lshlrev_b32_e32 v127, 7, v123
	v_and_b32_e32 v129, 8, v0
	s_addc_u32 s9, s61, 0
	v_and_b32_e32 v130, 0x3f0, v4
	v_add3_u32 v131, 0, v3, v2
	v_mov_b64_e32 v[102:103], s[62:63]
	v_lshlrev_b32_e32 v0, 1, v0
	s_mov_b32 s45, s26
	s_branch .LBB0_241

; DI float bf2f(short s) { return __uint_as_float(((unsigned)(unsigned short)s) << 16); }
; template <bool ROPE>
; DI void q_prep(bf16x8& q0, bf16x8& q1, const float* gq, int g, const float* rope, int t) {
;     float x[16]; float ss = 0.f;
; #pragma unroll
;     for (int e = 0; e < 8; ++e) { x[e] = bf2f(q0[e]); x[8 + e] = bf2f(q1[e]); ss += x[e] * x[e] + x[8 + e] * x[8 + e]; }
;     ss += __shfl_xor(ss, 16); ss += __shfl_xor(ss, 32);
;     const float rstd = rsqrtf(ss * (1.0f / 64.0f) + EPS);
;     const f32x4 ga = *(const f32x4*)(gq + 8 * g), gb = *(const f32x4*)(gq + 8 * g + 4), gc = *(const f32x4*)(gq + 32 + 8 * g), gd = *(const f32x4*)(gq + 32 + 8 * g + 4);
; #pragma unroll
;     for (int e = 0; e < 4; ++e) { x[e] *= rstd * ga[e]; x[4 + e] *= rstd * gb[e]; x[8 + e] *= rstd * gc[e]; x[12 + e] *= rstd * gd[e]; }
; DI void attn_odd_lds(Frame& F, const float* gk  , const float* gq  , bool with_ctx) {
;     ...
;     for (int item = F.vcu; item < NB * 2 * 32 + (with_ctx ? NB * 2 * 2 : 0); item += F.G) {
;         const bool isc = item >= NB * 2 * 32; const int ci = item - NB * 2 * 32;
;         const int b = isc ? (ci >> 2) : (item >> 6), kvh = isc ? ((ci >> 1) & 1) : ((item >> 5) & 1);
;         const int tq = isc ? (ci & 1) * 128 : (item & 31) * 128;
;         const int qbase = (isc ? TL + b * CTXL : b * SEQ) + tq + F.wave * 16;
;         const int nlat = isc ? 0 : 64;
;         const int qrow = qbase + l16;
;         const bf16_t* qp = P + (size_t)qrow * kp + kvh * 256 + g * 8;
;         bf16x8 q[4][2]; f32x4 o[4][4]; float mx[4], ls[4];
; #pragma unroll
;         for (int h = 0; h < 4; ++h) { q[h][0] = *(const bf16x8*)(qp + h * 64); q[h][1] = *(const bf16x8*)(qp + h * 64 + 32); { int gl_ = g; asm volatile("" : "+v"(gl_)); if (isc) q_prep<false>(q[h][0], q[h][1], gq, gl_, nullptr, 0); else q_prep<true>(q[h][0], q[h][1], gq, gl_, WSP(float, WS_ROPE), tq + F.wave * 16 + l16); } mx[h] = q_norm(q[h][0], q[h][1]) * kn; ls[h] = 0.f;
.LBB0_241:
	s_add_i32 s4, s84, 0xfffffc00
	s_ashr_i32 s10, s4, 2
	s_ashr_i32 s11, s84, 6
	s_cmpk_lt_i32 s84, 0x400
	s_cselect_b64 s[4:5], -1, 0
	s_and_b64 s[4:5], s[4:5], exec
	s_cselect_b32 s4, s11, s10
	s_lshl_b32 s70, s4, 8
	s_add_i32 s10, s70, 0x10000
	s_lshl_b32 s72, s4, 12
	s_cmpk_lt_i32 s84, 0x400
	s_cselect_b64 s[4:5], -1, 0
	s_and_b64 s[4:5], s[4:5], exec
	s_cselect_b32 s4, s72, s10
	s_lshl_b32 s5, s84, 7
	s_and_b32 s11, s5, 0x80
	s_and_b32 s36, s5, 0xf80
	s_cmpk_lt_i32 s84, 0x400
	s_cselect_b64 s[68:69], -1, 0
	s_and_b64 vcc, s[68:69], exec
	s_cselect_b32 s5, 5, 1
	s_cselect_b32 s12, s36, s11
	s_cmpk_gt_i32 s84, 0x3ff
	s_cselect_b64 s[74:75], -1, 0
	s_add_i32 s85, s12, s83
	s_lshr_b32 s5, s84, s5
	s_add_i32 s85, s85, s4
	s_and_b32 s11, s5, 1
	v_or_b32_e32 v2, s85, v122
	s_movk_i32 s4, 0xe00
	v_mad_i64_i32 v[2:3], s[4:5], v2, s4, v[102:103]
	s_lshl_b32 s20, s11, 9
	v_lshl_add_u64 v[2:3], v[2:3], 0, s[20:21]
	v_lshl_add_u64 v[26:27], v[2:3], 0, v[0:1]
	global_load_dwordx4 v[6:9], v[26:27], off
	global_load_dwordx4 v[18:21], v[26:27], off offset:64
	v_mov_b32_e32 v4, v123
	s_mov_b64 s[4:5], -1
	v_lshlrev_b32_e32 v2, 3, v4
	v_ashrrev_i32_e32 v3, 31, v2
	s_waitcnt vmcnt(1)
	v_and_b32_e32 v13, 0xffff0000, v9
	v_lshlrev_b32_e32 v12, 16, v9
	s_waitcnt vmcnt(0)
	v_and_b32_e32 v11, 0xffff0000, v21
	v_lshlrev_b32_e32 v10, 16, v21
	v_and_b32_e32 v17, 0xffff0000, v20
	v_lshlrev_b32_e32 v16, 16, v20
	v_and_b32_e32 v15, 0xffff0000, v19
	v_lshlrev_b32_e32 v14, 16, v19
	v_and_b32_e32 v21, 0xffff0000, v18
	v_lshlrev_b32_e32 v20, 16, v18
	v_and_b32_e32 v23, 0xffff0000, v8
	v_lshlrev_b32_e32 v22, 16, v8
	v_and_b32_e32 v19, 0xffff0000, v7
	v_lshlrev_b32_e32 v18, 16, v7
	v_and_b32_e32 v25, 0xffff0000, v6
	v_lshlrev_b32_e32 v24, 16, v6
	s_cbranch_vccnz .LBB0_243
	v_lshl_add_u64 v[36:37], v[2:3], 2, s[6:7]
	global_load_dwordx4 v[6:9], v[36:37], off
	global_load_dwordx4 v[28:31], v[36:37], off offset:16
	global_load_dwordx4 v[32:35], v[36:37], off offset:128
	s_nop 0
	global_load_dwordx4 v[36:39], v[36:37], off offset:144
	v_pk_mul_f32 v[46:47], v[20:21], v[20:21]
	v_pk_mul_f32 v[44:45], v[14:15], v[14:15]
	v_pk_fma_f32 v[46:47], v[24:25], v[24:25], v[46:47]
	v_pk_fma_f32 v[44:45], v[18:19], v[18:19], v[44:45]
	v_add_f32_e32 v5, v46, v47
	v_pk_mul_f32 v[42:43], v[16:17], v[16:17]
	v_add_f32_e32 v5, v44, v5
	v_pk_fma_f32 v[42:43], v[22:23], v[22:23], v[42:43]
	v_add_f32_e32 v5, v45, v5
	v_pk_mul_f32 v[40:41], v[10:11], v[10:11]
	v_add_f32_e32 v5, v42, v5
	v_pk_fma_f32 v[40:41], v[12:13], v[12:13], v[40:41]
	v_add_f32_e32 v5, v43, v5
	v_add_f32_e32 v5, v40, v5
	v_add_f32_e32 v5, v41, v5
	ds_bpermute_b32 v40, v120, v5
	s_mov_b64 s[4:5], 0
	s_waitcnt lgkmcnt(0)
	v_add_f32_e32 v5, v5, v40
	ds_bpermute_b32 v40, v121, v5
	s_waitcnt lgkmcnt(0)
	v_add_f32_e32 v5, v5, v40
	v_fmamk_f32 v5, v5, 0x3c800000, v162
	v_mul_f32_e32 v40, 0x4b800000, v5
	v_cmp_gt_f32_e32 vcc, s27, v5
	s_nop 1
	v_cndmask_b32_e32 v5, v5, v40, vcc
	v_rsq_f32_e32 v5, v5
	s_nop 0
	v_mul_f32_e32 v40, 0x45800000, v5
	v_cndmask_b32_e32 v40, v5, v40, vcc
	v_mul_f32_e32 v40, 0x3e38aa3b, v40
	s_waitcnt vmcnt(3)
	v_pk_mul_f32 v[6:7], v[6:7], v[40:41] op_sel_hi:[1,0]
	s_waitcnt vmcnt(2)
	v_pk_mul_f32 v[42:43], v[28:29], v[40:41] op_sel_hi:[1,0]
	s_waitcnt vmcnt(1)
	v_pk_mul_f32 v[32:33], v[32:33], v[40:41] op_sel_hi:[1,0]
	s_waitcnt vmcnt(0)
	v_pk_mul_f32 v[36:37], v[36:37], v[40:41] op_sel_hi:[1,0]
	v_pk_mul_f32 v[8:9], v[8:9], v[40:41] op_sel_hi:[1,0]
	v_pk_mul_f32 v[44:45], v[30:31], v[40:41] op_sel_hi:[1,0]
	v_pk_mul_f32 v[46:47], v[34:35], v[40:41] op_sel_hi:[1,0]
	v_pk_mul_f32 v[38:39], v[38:39], v[40:41] op_sel_hi:[1,0]
	v_pk_mul_f32 v[28:29], v[6:7], v[24:25]
	v_pk_mul_f32 v[30:31], v[42:43], v[22:23]
	v_pk_mul_f32 v[6:7], v[32:33], v[20:21]
	v_pk_mul_f32 v[36:37], v[36:37], v[16:17]
	v_pk_mul_f32 v[32:33], v[8:9], v[18:19]
	v_pk_mul_f32 v[34:35], v[44:45], v[12:13]
	v_pk_mul_f32 v[8:9], v[46:47], v[14:15]
	v_pk_mul_f32 v[38:39], v[38:39], v[10:11]
.LBB0_243:
	s_andn2_b64 vcc, exec, s[4:5]
	s_cbranch_vccnz .LBB0_245
	v_lshl_add_u64 v[2:3], v[2:3], 2, s[6:7]
	global_load_dwordx4 v[28:31], v[2:3], off offset:16
	global_load_dwordx4 v[32:35], v[2:3], off
	global_load_dwordx4 v[36:39], v[2:3], off offset:144
	global_load_dwordx4 v[40:43], v[2:3], off offset:128
	s_add_i32 s4, s36, s83
	s_ashr_i32 s4, s4, 2
	s_and_b32 s4, s4, 0x7ffffff0
	v_lshlrev_b32_e32 v4, 2, v4
	v_add_lshl_u32 v2, s4, v4, 1
	v_add_lshl_u32 v4, v4, v130, 1
	v_ashrrev_i32_e32 v3, 31, v2
	v_ashrrev_i32_e32 v5, 31, v4
	v_lshl_add_u64 v[2:3], v[2:3], 2, s[8:9]
	v_lshl_add_u64 v[6:7], v[4:5], 2, s[8:9]
	global_load_dwordx4 v[44:47], v[2:3], off offset:16
	global_load_dwordx4 v[48:51], v[2:3], off
	s_nop 0
	global_load_dwordx4 v[2:5], v[6:7], off offset:16
	s_nop 0
	global_load_dwordx4 v[6:9], v[6:7], off
	v_pk_mul_f32 v[52:53], v[20:21], v[20:21]
	v_pk_mul_f32 v[54:55], v[14:15], v[14:15]
	v_pk_fma_f32 v[52:53], v[24:25], v[24:25], v[52:53]
	v_pk_fma_f32 v[54:55], v[18:19], v[18:19], v[54:55]
	v_add_f32_e32 v52, v52, v53
	v_pk_mul_f32 v[56:57], v[16:17], v[16:17]
	v_add_f32_e32 v52, v54, v52
	v_pk_fma_f32 v[56:57], v[22:23], v[22:23], v[56:57]
	v_add_f32_e32 v52, v55, v52
	v_pk_mul_f32 v[58:59], v[10:11], v[10:11]
	v_add_f32_e32 v52, v56, v52
	v_pk_fma_f32 v[58:59], v[12:13], v[12:13], v[58:59]
	v_add_f32_e32 v52, v57, v52
	v_add_f32_e32 v52, v58, v52
	v_add_f32_e32 v52, v59, v52
	ds_bpermute_b32 v53, v120, v52
	s_waitcnt lgkmcnt(0)
	v_add_f32_e32 v52, v52, v53
	ds_bpermute_b32 v53, v121, v52
	s_waitcnt lgkmcnt(0)
; DI unsigned pk2(float lo, float hi) { f32x2 v = {lo, hi}; bf16x2_t b = __builtin_convertvector(v, bf16x2_t); return __builtin_bit_cast(unsigned, b); }
; DI float bf2f(short s) { return __uint_as_float(((unsigned)(unsigned short)s) << 16); }
; template <bool ROPE>
; DI void q_prep(bf16x8& q0, bf16x8& q1, const float* gq, int g, const float* rope, int t) {
;     ...
;     if (ROPE) {
;         const float* rr = rope + ((t >> 6) * 16 + 4 * g) * 2; const float* rc = rope + ((t & 63) * 16 + 4 * g) * 2;
;         const f32x4 r0 = *(const f32x4*)rr, r1 = *(const f32x4*)(rr + 4), c0 = *(const f32x4*)rc, c1 = *(const f32x4*)(rc + 4);
;         const float cs[8] = {r0[0], r0[2], r1[0], r1[2], c0[0], c0[2], c1[0], c1[2]}, sn[8] = {r0[1], r0[3], r1[1], r1[3], c0[1], c0[3], c1[1], c1[3]};
; #pragma unroll
;         for (int i = 0; i < 8; ++i) { const float a = x[2 * i], b = x[2 * i + 1]; x[2 * i] = a * cs[i] - b * sn[i]; x[2 * i + 1] = a * sn[i] + b * cs[i]; }
;     }
;     u32x4 w0, w1; w0.x = pk2(x[0], x[1]); w0.y = pk2(x[2], x[3]); w0.z = pk2(x[4], x[5]); w0.w = pk2(x[6], x[7]); w1.x = pk2(x[8], x[9]); w1.y = pk2(x[10], x[11]); w1.z = pk2(x[12], x[13]); w1.w = pk2(x[14], x[15]);
;     q0 = __builtin_bit_cast(bf16x8, w0); q1 = __builtin_bit_cast(bf16x8, w1);
; DI float q_norm(bf16x8 q0, bf16x8 q1) {
;     float ss = 0.f;
; #pragma unroll
;     for (int e = 0; e < 8; ++e) { const float a = bf2f(q0[e]), b = bf2f(q1[e]); ss += a * a + b * b; }
;     ss += __shfl_xor(ss, 16); ss += __shfl_xor(ss, 32);
;     return sqrtf(ss);
; }
	v_add_f32_e32 v52, v52, v53
	v_fmamk_f32 v52, v52, 0x3c800000, v162
	v_cmp_gt_f32_e32 vcc, s27, v52
	v_mul_f32_e32 v53, 0x4b800000, v52
	s_nop 0
	v_cndmask_b32_e32 v52, v52, v53, vcc
	v_rsq_f32_e32 v52, v52
	s_nop 0
	v_mul_f32_e32 v53, 0x45800000, v52
	v_cndmask_b32_e32 v52, v52, v53, vcc
	v_mul_f32_e32 v52, 0x3e38aa3b, v52
	s_waitcnt vmcnt(7)
	v_pk_mul_f32 v[28:29], v[28:29], v[52:53] op_sel_hi:[1,0]
	s_nop 0
	v_pk_mul_f32 v[22:23], v[28:29], v[22:23]
	s_waitcnt vmcnt(6)
	v_pk_mul_f32 v[32:33], v[32:33], v[52:53] op_sel_hi:[1,0]
	s_waitcnt vmcnt(4)
	v_pk_mul_f32 v[28:29], v[40:41], v[52:53] op_sel_hi:[1,0]
	v_pk_mul_f32 v[24:25], v[32:33], v[24:25]
	v_pk_mul_f32 v[20:21], v[28:29], v[20:21]
	v_pk_mul_f32 v[28:29], v[36:37], v[52:53] op_sel_hi:[1,0]
	s_waitcnt vmcnt(2)
	v_pk_mul_f32 v[40:41], v[48:49], v[24:25]
	v_pk_mul_f32 v[16:17], v[28:29], v[16:17]
	v_pk_mul_f32 v[28:29], v[34:35], v[52:53] op_sel_hi:[1,0]
	s_nop 0
	v_pk_mul_f32 v[18:19], v[28:29], v[18:19]
	v_pk_mul_f32 v[28:29], v[30:31], v[52:53] op_sel_hi:[1,0]
	s_nop 0
	v_pk_mul_f32 v[12:13], v[28:29], v[12:13]
	v_pk_mul_f32 v[28:29], v[42:43], v[52:53] op_sel_hi:[1,0]
	s_nop 0
	v_pk_mul_f32 v[14:15], v[28:29], v[14:15]
	v_pk_mul_f32 v[28:29], v[38:39], v[52:53] op_sel_hi:[1,0]
	s_nop 0
	v_pk_mul_f32 v[10:11], v[28:29], v[10:11]
	v_mul_f32_e32 v28, v49, v24
	v_pk_fma_f32 v[28:29], v[48:49], v[24:25], v[28:29] op_sel:[1,0,0] op_sel_hi:[0,1,0]
	v_mul_f32_e32 v28, v51, v18
	v_pk_fma_f32 v[32:33], v[50:51], v[18:19], v[28:29] op_sel:[1,0,0] op_sel_hi:[0,1,0]
	v_mul_f32_e32 v28, v45, v22
	v_pk_fma_f32 v[30:31], v[44:45], v[22:23], v[28:29] op_sel:[1,0,0] op_sel_hi:[0,1,0]
	v_mul_f32_e32 v28, v47, v12
	v_pk_fma_f32 v[34:35], v[46:47], v[12:13], v[28:29] op_sel:[1,0,0] op_sel_hi:[0,1,0]
	s_waitcnt vmcnt(0)
	v_mul_f32_e32 v28, v7, v20
	v_pk_mul_f32 v[24:25], v[50:51], v[18:19]
	v_pk_mul_f32 v[18:19], v[44:45], v[22:23]
	v_pk_mul_f32 v[22:23], v[46:47], v[12:13]
	v_pk_mul_f32 v[12:13], v[6:7], v[20:21]
	v_pk_fma_f32 v[6:7], v[6:7], v[20:21], v[28:29] op_sel:[1,0,0] op_sel_hi:[0,1,0]
	v_mul_f32_e32 v6, v9, v14
	v_pk_mul_f32 v[20:21], v[8:9], v[14:15]
	v_pk_fma_f32 v[8:9], v[8:9], v[14:15], v[6:7] op_sel:[1,0,0] op_sel_hi:[0,1,0]
	v_mul_f32_e32 v6, v3, v16
	v_pk_fma_f32 v[36:37], v[2:3], v[16:17], v[6:7] op_sel:[1,0,0] op_sel_hi:[0,1,0]
	v_mul_f32_e32 v6, v5, v10
	v_pk_mul_f32 v[14:15], v[2:3], v[16:17]
	v_pk_mul_f32 v[2:3], v[4:5], v[10:11]
	v_pk_fma_f32 v[38:39], v[4:5], v[10:11], v[6:7] op_sel:[1,0,0] op_sel_hi:[0,1,0]
	v_sub_f32_e32 v28, v40, v41
	v_sub_f32_e32 v32, v24, v25
	v_sub_f32_e32 v30, v18, v19
	v_sub_f32_e32 v34, v22, v23
	v_sub_f32_e32 v6, v12, v13
	v_sub_f32_e32 v8, v20, v21
	v_sub_f32_e32 v36, v14, v15
	v_sub_f32_e32 v38, v2, v3
.LBB0_245:
	global_load_dwordx4 v[14:17], v[26:27], off offset:128
	global_load_dwordx4 v[40:43], v[26:27], off offset:192
	v_cvt_pk_bf16_f32 v6, v6, v7
	v_cvt_pk_bf16_f32 v2, v28, v29
	v_cvt_pk_bf16_f32 v7, v8, v9
	v_lshlrev_b32_e32 v13, 16, v6
	v_and_b32_e32 v19, 0xffff0000, v6
	v_cvt_pk_bf16_f32 v3, v32, v33
	v_lshlrev_b32_e32 v11, 16, v2
	v_and_b32_e32 v18, 0xffff0000, v2
	v_lshlrev_b32_e32 v21, 16, v7
	v_mul_f32_e32 v13, v13, v13
	v_mul_f32_e32 v19, v19, v19
	v_cvt_pk_bf16_f32 v8, v36, v37
	v_lshlrev_b32_e32 v20, 16, v3
	v_and_b32_e32 v23, 0xffff0000, v7
	v_mul_f32_e32 v21, v21, v21
	v_fmac_f32_e32 v13, v11, v11
	v_fmac_f32_e32 v19, v18, v18
	v_cvt_pk_bf16_f32 v4, v30, v31
	v_and_b32_e32 v22, 0xffff0000, v3
	v_lshlrev_b32_e32 v25, 16, v8
	v_mul_f32_e32 v23, v23, v23
	v_fmac_f32_e32 v21, v20, v20
	v_add_f32_e32 v11, v13, v19
	v_cvt_pk_bf16_f32 v9, v38, v39
	v_lshlrev_b32_e32 v24, 16, v4
	v_and_b32_e32 v29, 0xffff0000, v8
	v_mul_f32_e32 v25, v25, v25
	v_fmac_f32_e32 v23, v22, v22
	v_add_f32_e32 v11, v21, v11
	v_cvt_pk_bf16_f32 v5, v34, v35
	v_and_b32_e32 v28, 0xffff0000, v4
	v_lshlrev_b32_e32 v31, 16, v9
	v_mul_f32_e32 v29, v29, v29
	v_fmac_f32_e32 v25, v24, v24
	v_add_f32_e32 v11, v23, v11
	v_lshlrev_b32_e32 v30, 16, v5
	v_and_b32_e32 v33, 0xffff0000, v9
	v_mul_f32_e32 v31, v31, v31
	v_fmac_f32_e32 v29, v28, v28
	v_add_f32_e32 v11, v25, v11
	v_and_b32_e32 v32, 0xffff0000, v5
	v_mul_f32_e32 v33, v33, v33
	v_fmac_f32_e32 v31, v30, v30
	v_add_f32_e32 v11, v29, v11
	v_fmac_f32_e32 v33, v32, v32
	v_add_f32_e32 v11, v31, v11
	v_add_f32_e32 v13, v33, v11
	ds_bpermute_b32 v18, v120, v13
	v_mov_b32_e32 v12, v123
	v_cndmask_b32_e64 v10, 0, 1, s[74:75]
	v_cmp_ne_u32_e64 s[4:5], 1, v10
	s_waitcnt lgkmcnt(0)
	v_add_f32_e32 v60, v13, v18
	ds_bpermute_b32 v61, v121, v60
	v_lshlrev_b32_e32 v10, 3, v12
	s_mov_b64 s[76:77], -1
	s_andn2_b64 vcc, exec, s[74:75]
	v_ashrrev_i32_e32 v11, 31, v10
	s_waitcnt vmcnt(1)
	v_and_b32_e32 v23, 0xffff0000, v17
	v_lshlrev_b32_e32 v22, 16, v17
	s_waitcnt vmcnt(0)
	v_and_b32_e32 v19, 0xffff0000, v43
	v_lshlrev_b32_e32 v18, 16, v43
	v_and_b32_e32 v25, 0xffff0000, v42
	v_lshlrev_b32_e32 v24, 16, v42
	v_and_b32_e32 v21, 0xffff0000, v41
	v_lshlrev_b32_e32 v20, 16, v41
	v_and_b32_e32 v31, 0xffff0000, v40
	v_lshlrev_b32_e32 v30, 16, v40
	v_and_b32_e32 v33, 0xffff0000, v16
	v_lshlrev_b32_e32 v32, 16, v16
	v_and_b32_e32 v29, 0xffff0000, v15
	v_lshlrev_b32_e32 v28, 16, v15
	v_and_b32_e32 v35, 0xffff0000, v14
	v_lshlrev_b32_e32 v34, 16, v14
	s_cbranch_vccnz .LBB0_247
; DI unsigned pk2(float lo, float hi) { f32x2 v = {lo, hi}; bf16x2_t b = __builtin_convertvector(v, bf16x2_t); return __builtin_bit_cast(unsigned, b); }
; DI float bf2f(short s) { return __uint_as_float(((unsigned)(unsigned short)s) << 16); }
; template <bool ROPE>
; DI void q_prep(bf16x8& q0, bf16x8& q1, const float* gq, int g, const float* rope, int t) {
;     float x[16]; float ss = 0.f;
; #pragma unroll
;     for (int e = 0; e < 8; ++e) { x[e] = bf2f(q0[e]); x[8 + e] = bf2f(q1[e]); ss += x[e] * x[e] + x[8 + e] * x[8 + e]; }
;     ss += __shfl_xor(ss, 16); ss += __shfl_xor(ss, 32);
;     const float rstd = rsqrtf(ss * (1.0f / 64.0f) + EPS);
;     const f32x4 ga = *(const f32x4*)(gq + 8 * g), gb = *(const f32x4*)(gq + 8 * g + 4), gc = *(const f32x4*)(gq + 32 + 8 * g), gd = *(const f32x4*)(gq + 32 + 8 * g + 4);
; #pragma unroll
;     for (int e = 0; e < 4; ++e) { x[e] *= rstd * ga[e]; x[4 + e] *= rstd * gb[e]; x[8 + e] *= rstd * gc[e]; x[12 + e] *= rstd * gd[e]; }
;     if (ROPE) {
;         const float* rr = rope + ((t >> 6) * 16 + 4 * g) * 2; const float* rc = rope + ((t & 63) * 16 + 4 * g) * 2;
;         const f32x4 r0 = *(const f32x4*)rr, r1 = *(const f32x4*)(rr + 4), c0 = *(const f32x4*)rc, c1 = *(const f32x4*)(rc + 4);
;         const float cs[8] = {r0[0], r0[2], r1[0], r1[2], c0[0], c0[2], c1[0], c1[2]}, sn[8] = {r0[1], r0[3], r1[1], r1[3], c0[1], c0[3], c1[1], c1[3]};
; #pragma unroll
;         for (int i = 0; i < 8; ++i) { const float a = x[2 * i], b = x[2 * i + 1]; x[2 * i] = a * cs[i] - b * sn[i]; x[2 * i + 1] = a * sn[i] + b * cs[i]; }
;     }
;     u32x4 w0, w1; w0.x = pk2(x[0], x[1]); w0.y = pk2(x[2], x[3]); w0.z = pk2(x[4], x[5]); w0.w = pk2(x[6], x[7]); w1.x = pk2(x[8], x[9]); w1.y = pk2(x[10], x[11]); w1.z = pk2(x[12], x[13]); w1.w = pk2(x[14], x[15]);
;     q0 = __builtin_bit_cast(bf16x8, w0); q1 = __builtin_bit_cast(bf16x8, w1);
	v_lshl_add_u64 v[44:45], v[10:11], 2, s[6:7]
	global_load_dwordx4 v[14:17], v[44:45], off
	global_load_dwordx4 v[36:39], v[44:45], off offset:16
	global_load_dwordx4 v[40:43], v[44:45], off offset:128
	s_nop 0
	global_load_dwordx4 v[44:47], v[44:45], off offset:144
	v_pk_mul_f32 v[54:55], v[30:31], v[30:31]
	v_pk_mul_f32 v[52:53], v[20:21], v[20:21]
	v_pk_fma_f32 v[54:55], v[34:35], v[34:35], v[54:55]
	v_pk_fma_f32 v[52:53], v[28:29], v[28:29], v[52:53]
	v_add_f32_e32 v13, v54, v55
	v_pk_mul_f32 v[50:51], v[24:25], v[24:25]
	v_add_f32_e32 v13, v52, v13
	v_pk_fma_f32 v[50:51], v[32:33], v[32:33], v[50:51]
	v_add_f32_e32 v13, v53, v13
	v_pk_mul_f32 v[48:49], v[18:19], v[18:19]
	v_add_f32_e32 v13, v50, v13
	v_pk_fma_f32 v[48:49], v[22:23], v[22:23], v[48:49]
	v_add_f32_e32 v13, v51, v13
	v_add_f32_e32 v13, v48, v13
	v_add_f32_e32 v13, v49, v13
	ds_bpermute_b32 v48, v120, v13
	s_mov_b64 s[76:77], 0
	s_waitcnt lgkmcnt(0)
	v_add_f32_e32 v13, v13, v48
	ds_bpermute_b32 v48, v121, v13
	s_waitcnt lgkmcnt(0)
	v_add_f32_e32 v13, v13, v48
	v_fmamk_f32 v13, v13, 0x3c800000, v162
	v_mul_f32_e32 v48, 0x4b800000, v13
	v_cmp_gt_f32_e32 vcc, s27, v13
	s_nop 1
	v_cndmask_b32_e32 v13, v13, v48, vcc
	v_rsq_f32_e32 v13, v13
	s_nop 0
	v_mul_f32_e32 v48, 0x45800000, v13
	v_cndmask_b32_e32 v48, v13, v48, vcc
	v_mul_f32_e32 v48, 0x3e38aa3b, v48
	s_waitcnt vmcnt(3)
	v_pk_mul_f32 v[14:15], v[14:15], v[48:49] op_sel_hi:[1,0]
	s_waitcnt vmcnt(2)
	v_pk_mul_f32 v[50:51], v[36:37], v[48:49] op_sel_hi:[1,0]
	s_waitcnt vmcnt(1)
	v_pk_mul_f32 v[40:41], v[40:41], v[48:49] op_sel_hi:[1,0]
	s_waitcnt vmcnt(0)
	v_pk_mul_f32 v[44:45], v[44:45], v[48:49] op_sel_hi:[1,0]
	v_pk_mul_f32 v[16:17], v[16:17], v[48:49] op_sel_hi:[1,0]
	v_pk_mul_f32 v[52:53], v[38:39], v[48:49] op_sel_hi:[1,0]
	v_pk_mul_f32 v[54:55], v[42:43], v[48:49] op_sel_hi:[1,0]
	v_pk_mul_f32 v[46:47], v[46:47], v[48:49] op_sel_hi:[1,0]
	v_pk_mul_f32 v[36:37], v[14:15], v[34:35]
	v_pk_mul_f32 v[38:39], v[50:51], v[32:33]
	v_pk_mul_f32 v[14:15], v[40:41], v[30:31]
	v_pk_mul_f32 v[44:45], v[44:45], v[24:25]
	v_pk_mul_f32 v[40:41], v[16:17], v[28:29]
	v_pk_mul_f32 v[42:43], v[52:53], v[22:23]
	v_pk_mul_f32 v[16:17], v[54:55], v[20:21]
	v_pk_mul_f32 v[46:47], v[46:47], v[18:19]
.LBB0_247:
	s_andn2_b64 vcc, exec, s[76:77]
	s_cbranch_vccnz .LBB0_249
	v_lshl_add_u64 v[10:11], v[10:11], 2, s[6:7]
	global_load_dwordx4 v[36:39], v[10:11], off offset:16
	global_load_dwordx4 v[40:43], v[10:11], off
	global_load_dwordx4 v[44:47], v[10:11], off offset:144
	global_load_dwordx4 v[48:51], v[10:11], off offset:128
	s_add_i32 s12, s36, s83
	s_ashr_i32 s12, s12, 2
	s_and_b32 s12, s12, 0x7ffffff0
	v_lshlrev_b32_e32 v12, 2, v12
	v_add_lshl_u32 v10, v12, s12, 1
	v_add_lshl_u32 v12, v12, v130, 1
	v_ashrrev_i32_e32 v11, 31, v10
	v_ashrrev_i32_e32 v13, 31, v12
	v_lshl_add_u64 v[10:11], v[10:11], 2, s[8:9]
	v_lshl_add_u64 v[14:15], v[12:13], 2, s[8:9]
	global_load_dwordx4 v[52:55], v[10:11], off offset:16
	global_load_dwordx4 v[56:59], v[10:11], off
	s_nop 0
	global_load_dwordx4 v[10:13], v[14:15], off offset:16
	s_nop 0
	global_load_dwordx4 v[14:17], v[14:15], off
	v_pk_mul_f32 v[62:63], v[30:31], v[30:31]
	v_pk_mul_f32 v[64:65], v[20:21], v[20:21]
	v_pk_fma_f32 v[62:63], v[34:35], v[34:35], v[62:63]
	v_pk_fma_f32 v[64:65], v[28:29], v[28:29], v[64:65]
	v_add_f32_e32 v62, v62, v63
	v_pk_mul_f32 v[66:67], v[24:25], v[24:25]
	v_add_f32_e32 v62, v64, v62
	v_pk_fma_f32 v[66:67], v[32:33], v[32:33], v[66:67]
	v_add_f32_e32 v62, v65, v62
	v_pk_mul_f32 v[68:69], v[18:19], v[18:19]
	v_add_f32_e32 v62, v66, v62
	v_pk_fma_f32 v[68:69], v[22:23], v[22:23], v[68:69]
	v_add_f32_e32 v62, v67, v62
	v_add_f32_e32 v62, v68, v62
	v_add_f32_e32 v62, v69, v62
	ds_bpermute_b32 v63, v120, v62
	s_waitcnt lgkmcnt(0)
	v_add_f32_e32 v62, v62, v63
	ds_bpermute_b32 v63, v121, v62
	s_waitcnt lgkmcnt(0)
	v_add_f32_e32 v62, v62, v63
	v_fmamk_f32 v62, v62, 0x3c800000, v162
	v_cmp_gt_f32_e32 vcc, s27, v62
	v_mul_f32_e32 v63, 0x4b800000, v62
	s_nop 0
	v_cndmask_b32_e32 v62, v62, v63, vcc
	v_rsq_f32_e32 v62, v62
	s_nop 0
	v_mul_f32_e32 v63, 0x45800000, v62
	v_cndmask_b32_e32 v62, v62, v63, vcc
	v_mul_f32_e32 v62, 0x3e38aa3b, v62
	s_waitcnt vmcnt(7)
	v_pk_mul_f32 v[36:37], v[36:37], v[62:63] op_sel_hi:[1,0]
	s_nop 0
	v_pk_mul_f32 v[32:33], v[36:37], v[32:33]
	s_waitcnt vmcnt(6)
	v_pk_mul_f32 v[40:41], v[40:41], v[62:63] op_sel_hi:[1,0]
	s_waitcnt vmcnt(4)
	v_pk_mul_f32 v[36:37], v[48:49], v[62:63] op_sel_hi:[1,0]
	v_pk_mul_f32 v[34:35], v[40:41], v[34:35]
	v_pk_mul_f32 v[30:31], v[36:37], v[30:31]
	v_pk_mul_f32 v[36:37], v[44:45], v[62:63] op_sel_hi:[1,0]
	s_waitcnt vmcnt(2)
	v_pk_mul_f32 v[48:49], v[56:57], v[34:35]
	v_pk_mul_f32 v[24:25], v[36:37], v[24:25]
	v_pk_mul_f32 v[36:37], v[42:43], v[62:63] op_sel_hi:[1,0]
	s_nop 0
	v_pk_mul_f32 v[28:29], v[36:37], v[28:29]
	v_pk_mul_f32 v[36:37], v[38:39], v[62:63] op_sel_hi:[1,0]
	s_nop 0
	v_pk_mul_f32 v[22:23], v[36:37], v[22:23]
	v_pk_mul_f32 v[36:37], v[50:51], v[62:63] op_sel_hi:[1,0]
	s_nop 0
	v_pk_mul_f32 v[20:21], v[36:37], v[20:21]
	v_pk_mul_f32 v[36:37], v[46:47], v[62:63] op_sel_hi:[1,0]
	s_nop 0
	v_pk_mul_f32 v[18:19], v[36:37], v[18:19]
	v_mul_f32_e32 v36, v57, v34
	v_pk_fma_f32 v[36:37], v[56:57], v[34:35], v[36:37] op_sel:[1,0,0] op_sel_hi:[0,1,0]
	v_mul_f32_e32 v36, v59, v28
	v_pk_fma_f32 v[40:41], v[58:59], v[28:29], v[36:37] op_sel:[1,0,0] op_sel_hi:[0,1,0]
	v_mul_f32_e32 v36, v53, v32
	v_pk_fma_f32 v[38:39], v[52:53], v[32:33], v[36:37] op_sel:[1,0,0] op_sel_hi:[0,1,0]
	v_mul_f32_e32 v36, v55, v22
	v_pk_fma_f32 v[42:43], v[54:55], v[22:23], v[36:37] op_sel:[1,0,0] op_sel_hi:[0,1,0]
	s_waitcnt vmcnt(0)
	v_mul_f32_e32 v36, v15, v30
	v_pk_mul_f32 v[34:35], v[58:59], v[28:29]
	v_pk_mul_f32 v[28:29], v[52:53], v[32:33]
	v_pk_mul_f32 v[32:33], v[54:55], v[22:23]
	v_pk_mul_f32 v[22:23], v[14:15], v[30:31]
	v_pk_fma_f32 v[14:15], v[14:15], v[30:31], v[36:37] op_sel:[1,0,0] op_sel_hi:[0,1,0]
	v_mul_f32_e32 v14, v17, v20
	v_pk_mul_f32 v[30:31], v[16:17], v[20:21]
	v_pk_fma_f32 v[16:17], v[16:17], v[20:21], v[14:15] op_sel:[1,0,0] op_sel_hi:[0,1,0]
	v_mul_f32_e32 v14, v11, v24
	v_pk_fma_f32 v[44:45], v[10:11], v[24:25], v[14:15] op_sel:[1,0,0] op_sel_hi:[0,1,0]
	v_mul_f32_e32 v14, v13, v18
	v_pk_mul_f32 v[20:21], v[10:11], v[24:25]
	v_pk_mul_f32 v[10:11], v[12:13], v[18:19]
	v_pk_fma_f32 v[46:47], v[12:13], v[18:19], v[14:15] op_sel:[1,0,0] op_sel_hi:[0,1,0]
	v_sub_f32_e32 v36, v48, v49
	v_sub_f32_e32 v40, v34, v35
	v_sub_f32_e32 v38, v28, v29
	v_sub_f32_e32 v42, v32, v33
	v_sub_f32_e32 v14, v22, v23
	v_sub_f32_e32 v16, v30, v31
	v_sub_f32_e32 v44, v20, v21
	v_sub_f32_e32 v46, v10, v11
; DI float bf2f(short s) { return __uint_as_float(((unsigned)(unsigned short)s) << 16); }
; template <bool ROPE>
; DI void q_prep(bf16x8& q0, bf16x8& q1, const float* gq, int g, const float* rope, int t) {
;     float x[16]; float ss = 0.f;
; #pragma unroll
;     for (int e = 0; e < 8; ++e) { x[e] = bf2f(q0[e]); x[8 + e] = bf2f(q1[e]); ss += x[e] * x[e] + x[8 + e] * x[8 + e]; }
;     ss += __shfl_xor(ss, 16); ss += __shfl_xor(ss, 32);
;     const float rstd = rsqrtf(ss * (1.0f / 64.0f) + EPS);
;     const f32x4 ga = *(const f32x4*)(gq + 8 * g), gb = *(const f32x4*)(gq + 8 * g + 4), gc = *(const f32x4*)(gq + 32 + 8 * g), gd = *(const f32x4*)(gq + 32 + 8 * g + 4);
; #pragma unroll
;     for (int e = 0; e < 4; ++e) { x[e] *= rstd * ga[e]; x[4 + e] *= rstd * gb[e]; x[8 + e] *= rstd * gc[e]; x[12 + e] *= rstd * gd[e]; }
; DI float q_norm(bf16x8 q0, bf16x8 q1) {
;     float ss = 0.f;
; #pragma unroll
;     for (int e = 0; e < 8; ++e) { const float a = bf2f(q0[e]), b = bf2f(q1[e]); ss += a * a + b * b; }
;     ss += __shfl_xor(ss, 16); ss += __shfl_xor(ss, 32);
;     return sqrtf(ss);
; }
.LBB0_249:
	global_load_dwordx4 v[22:25], v[26:27], off offset:256
	global_load_dwordx4 v[48:51], v[26:27], off offset:320
	v_cvt_pk_bf16_f32 v14, v14, v15
	v_cvt_pk_bf16_f32 v10, v36, v37
	v_cvt_pk_bf16_f32 v15, v16, v17
	v_lshlrev_b32_e32 v19, 16, v14
	v_and_b32_e32 v28, 0xffff0000, v14
	v_cvt_pk_bf16_f32 v11, v40, v41
	v_lshlrev_b32_e32 v18, 16, v10
	v_and_b32_e32 v21, 0xffff0000, v10
	v_lshlrev_b32_e32 v30, 16, v15
	v_mul_f32_e32 v19, v19, v19
	v_mul_f32_e32 v28, v28, v28
	v_cvt_pk_bf16_f32 v16, v44, v45
	v_lshlrev_b32_e32 v29, 16, v11
	v_and_b32_e32 v32, 0xffff0000, v15
	v_mul_f32_e32 v30, v30, v30
	v_fmac_f32_e32 v19, v18, v18
	v_fmac_f32_e32 v28, v21, v21
	v_cvt_pk_bf16_f32 v12, v38, v39
	v_and_b32_e32 v31, 0xffff0000, v11
	v_lshlrev_b32_e32 v34, 16, v16
	v_mul_f32_e32 v32, v32, v32
	v_fmac_f32_e32 v30, v29, v29
	v_add_f32_e32 v18, v19, v28
	v_cvt_pk_bf16_f32 v17, v46, v47
	v_lshlrev_b32_e32 v33, 16, v12
	v_and_b32_e32 v36, 0xffff0000, v16
	v_mul_f32_e32 v34, v34, v34
	v_fmac_f32_e32 v32, v31, v31
	v_add_f32_e32 v18, v30, v18
	v_cvt_pk_bf16_f32 v13, v42, v43
	v_and_b32_e32 v35, 0xffff0000, v12
	v_lshlrev_b32_e32 v38, 16, v17
	v_mul_f32_e32 v36, v36, v36
	v_fmac_f32_e32 v34, v33, v33
	v_add_f32_e32 v18, v32, v18
	v_lshlrev_b32_e32 v37, 16, v13
	v_and_b32_e32 v40, 0xffff0000, v17
	v_mul_f32_e32 v38, v38, v38
	v_fmac_f32_e32 v36, v35, v35
	v_add_f32_e32 v18, v34, v18
	v_and_b32_e32 v39, 0xffff0000, v13
	v_mul_f32_e32 v40, v40, v40
	v_fmac_f32_e32 v38, v37, v37
	v_add_f32_e32 v18, v36, v18
	v_fmac_f32_e32 v40, v39, v39
	v_add_f32_e32 v18, v38, v18
	v_add_f32_e32 v21, v40, v18
	ds_bpermute_b32 v28, v120, v21
	v_mov_b32_e32 v20, v123
	s_mov_b64 s[74:75], -1
	v_lshlrev_b32_e32 v18, 3, v20
	s_waitcnt lgkmcnt(0)
	v_add_f32_e32 v62, v21, v28
	ds_bpermute_b32 v63, v121, v62
	s_and_b64 vcc, exec, s[4:5]
	v_ashrrev_i32_e32 v19, 31, v18
	s_waitcnt vmcnt(1)
	v_and_b32_e32 v33, 0xffff0000, v25
	v_lshlrev_b32_e32 v32, 16, v25
	s_waitcnt vmcnt(0)
	v_and_b32_e32 v29, 0xffff0000, v51
	v_lshlrev_b32_e32 v28, 16, v51
	v_and_b32_e32 v35, 0xffff0000, v50
	v_lshlrev_b32_e32 v34, 16, v50
	v_and_b32_e32 v31, 0xffff0000, v49
	v_lshlrev_b32_e32 v30, 16, v49
	v_and_b32_e32 v39, 0xffff0000, v48
	v_lshlrev_b32_e32 v38, 16, v48
	v_and_b32_e32 v41, 0xffff0000, v24
	v_lshlrev_b32_e32 v40, 16, v24
	v_and_b32_e32 v37, 0xffff0000, v23
	v_lshlrev_b32_e32 v36, 16, v23
	v_and_b32_e32 v43, 0xffff0000, v22
	v_lshlrev_b32_e32 v42, 16, v22
	s_cbranch_vccnz .LBB0_251
	v_lshl_add_u64 v[52:53], v[18:19], 2, s[6:7]
	global_load_dwordx4 v[22:25], v[52:53], off
	global_load_dwordx4 v[44:47], v[52:53], off offset:16
	global_load_dwordx4 v[48:51], v[52:53], off offset:128
	s_nop 0
	global_load_dwordx4 v[52:55], v[52:53], off offset:144
	v_pk_mul_f32 v[66:67], v[38:39], v[38:39]
	v_pk_mul_f32 v[64:65], v[30:31], v[30:31]
	v_pk_fma_f32 v[66:67], v[42:43], v[42:43], v[66:67]
	v_pk_fma_f32 v[64:65], v[36:37], v[36:37], v[64:65]
	v_add_f32_e32 v21, v66, v67
	v_pk_mul_f32 v[58:59], v[34:35], v[34:35]
	v_add_f32_e32 v21, v64, v21
	v_pk_fma_f32 v[58:59], v[40:41], v[40:41], v[58:59]
	v_add_f32_e32 v21, v65, v21
	v_pk_mul_f32 v[56:57], v[28:29], v[28:29]
	v_add_f32_e32 v21, v58, v21
	v_pk_fma_f32 v[56:57], v[32:33], v[32:33], v[56:57]
	v_add_f32_e32 v21, v59, v21
	v_add_f32_e32 v21, v56, v21
	v_add_f32_e32 v21, v57, v21
	ds_bpermute_b32 v56, v120, v21
	s_mov_b64 s[74:75], 0
	s_waitcnt lgkmcnt(0)
	v_add_f32_e32 v21, v21, v56
	ds_bpermute_b32 v56, v121, v21
	s_waitcnt lgkmcnt(0)
	v_add_f32_e32 v21, v21, v56
	v_fmamk_f32 v21, v21, 0x3c800000, v162
	v_mul_f32_e32 v56, 0x4b800000, v21
	v_cmp_gt_f32_e32 vcc, s27, v21
	s_nop 1
	v_cndmask_b32_e32 v21, v21, v56, vcc
	v_rsq_f32_e32 v21, v21
	s_nop 0
	v_mul_f32_e32 v56, 0x45800000, v21
	v_cndmask_b32_e32 v56, v21, v56, vcc
	v_mul_f32_e32 v56, 0x3e38aa3b, v56
	s_waitcnt vmcnt(3)
	v_pk_mul_f32 v[22:23], v[22:23], v[56:57] op_sel_hi:[1,0]
	s_waitcnt vmcnt(2)
	v_pk_mul_f32 v[58:59], v[44:45], v[56:57] op_sel_hi:[1,0]
	s_waitcnt vmcnt(1)
	v_pk_mul_f32 v[48:49], v[48:49], v[56:57] op_sel_hi:[1,0]
	s_waitcnt vmcnt(0)
	v_pk_mul_f32 v[52:53], v[52:53], v[56:57] op_sel_hi:[1,0]
	v_pk_mul_f32 v[24:25], v[24:25], v[56:57] op_sel_hi:[1,0]
	v_pk_mul_f32 v[64:65], v[46:47], v[56:57] op_sel_hi:[1,0]
	v_pk_mul_f32 v[66:67], v[50:51], v[56:57] op_sel_hi:[1,0]
	v_pk_mul_f32 v[54:55], v[54:55], v[56:57] op_sel_hi:[1,0]
	v_pk_mul_f32 v[44:45], v[22:23], v[42:43]
	v_pk_mul_f32 v[46:47], v[58:59], v[40:41]
	v_pk_mul_f32 v[22:23], v[48:49], v[38:39]
	v_pk_mul_f32 v[52:53], v[52:53], v[34:35]
	v_pk_mul_f32 v[48:49], v[24:25], v[36:37]
	v_pk_mul_f32 v[50:51], v[64:65], v[32:33]
	v_pk_mul_f32 v[24:25], v[66:67], v[30:31]
	v_pk_mul_f32 v[54:55], v[54:55], v[28:29]
; DI unsigned pk2(float lo, float hi) { f32x2 v = {lo, hi}; bf16x2_t b = __builtin_convertvector(v, bf16x2_t); return __builtin_bit_cast(unsigned, b); }
; template <bool ROPE>
; DI void q_prep(bf16x8& q0, bf16x8& q1, const float* gq, int g, const float* rope, int t) {
;     ...
;     if (ROPE) {
;         const float* rr = rope + ((t >> 6) * 16 + 4 * g) * 2; const float* rc = rope + ((t & 63) * 16 + 4 * g) * 2;
;         const f32x4 r0 = *(const f32x4*)rr, r1 = *(const f32x4*)(rr + 4), c0 = *(const f32x4*)rc, c1 = *(const f32x4*)(rc + 4);
;         const float cs[8] = {r0[0], r0[2], r1[0], r1[2], c0[0], c0[2], c1[0], c1[2]}, sn[8] = {r0[1], r0[3], r1[1], r1[3], c0[1], c0[3], c1[1], c1[3]};
; #pragma unroll
;         for (int i = 0; i < 8; ++i) { const float a = x[2 * i], b = x[2 * i + 1]; x[2 * i] = a * cs[i] - b * sn[i]; x[2 * i + 1] = a * sn[i] + b * cs[i]; }
;     }
;     u32x4 w0, w1; w0.x = pk2(x[0], x[1]); w0.y = pk2(x[2], x[3]); w0.z = pk2(x[4], x[5]); w0.w = pk2(x[6], x[7]); w1.x = pk2(x[8], x[9]); w1.y = pk2(x[10], x[11]); w1.z = pk2(x[12], x[13]); w1.w = pk2(x[14], x[15]);
;     q0 = __builtin_bit_cast(bf16x8, w0); q1 = __builtin_bit_cast(bf16x8, w1);
.LBB0_251:
	s_andn2_b64 vcc, exec, s[74:75]
	s_cbranch_vccnz .LBB0_253
	v_lshl_add_u64 v[18:19], v[18:19], 2, s[6:7]
	global_load_dwordx4 v[44:47], v[18:19], off offset:16
	global_load_dwordx4 v[48:51], v[18:19], off
	global_load_dwordx4 v[52:55], v[18:19], off offset:144
	global_load_dwordx4 v[56:59], v[18:19], off offset:128
	s_add_i32 s12, s36, s83
	s_ashr_i32 s12, s12, 2
	s_and_b32 s12, s12, 0x7ffffff0
	v_lshlrev_b32_e32 v20, 2, v20
	v_add_lshl_u32 v18, v20, s12, 1
	v_add_lshl_u32 v20, v20, v130, 1
	v_ashrrev_i32_e32 v19, 31, v18
	v_ashrrev_i32_e32 v21, 31, v20
	v_lshl_add_u64 v[18:19], v[18:19], 2, s[8:9]
	v_lshl_add_u64 v[22:23], v[20:21], 2, s[8:9]
	global_load_dwordx4 v[64:67], v[18:19], off offset:16
	global_load_dwordx4 v[68:71], v[18:19], off
	s_nop 0
	global_load_dwordx4 v[18:21], v[22:23], off offset:16
	s_nop 0
	global_load_dwordx4 v[22:25], v[22:23], off
	v_pk_mul_f32 v[72:73], v[38:39], v[38:39]
	v_pk_mul_f32 v[74:75], v[30:31], v[30:31]
	v_pk_fma_f32 v[72:73], v[42:43], v[42:43], v[72:73]
	v_pk_fma_f32 v[74:75], v[36:37], v[36:37], v[74:75]
	v_add_f32_e32 v72, v72, v73
	v_pk_mul_f32 v[76:77], v[34:35], v[34:35]
	v_add_f32_e32 v72, v74, v72
	v_pk_fma_f32 v[76:77], v[40:41], v[40:41], v[76:77]
	v_add_f32_e32 v72, v75, v72
	v_pk_mul_f32 v[78:79], v[28:29], v[28:29]
	v_add_f32_e32 v72, v76, v72
	v_pk_fma_f32 v[78:79], v[32:33], v[32:33], v[78:79]
	v_add_f32_e32 v72, v77, v72
	v_add_f32_e32 v72, v78, v72
	v_add_f32_e32 v72, v79, v72
	ds_bpermute_b32 v73, v120, v72
	s_waitcnt lgkmcnt(0)
	v_add_f32_e32 v72, v72, v73
	ds_bpermute_b32 v73, v121, v72
	s_waitcnt lgkmcnt(0)
	v_add_f32_e32 v72, v72, v73
	v_fmamk_f32 v72, v72, 0x3c800000, v162
	v_cmp_gt_f32_e32 vcc, s27, v72
	v_mul_f32_e32 v73, 0x4b800000, v72
	s_nop 0
	v_cndmask_b32_e32 v72, v72, v73, vcc
	v_rsq_f32_e32 v72, v72
	s_nop 0
	v_mul_f32_e32 v73, 0x45800000, v72
	v_cndmask_b32_e32 v72, v72, v73, vcc
	v_mul_f32_e32 v72, 0x3e38aa3b, v72
	s_waitcnt vmcnt(7)
	v_pk_mul_f32 v[44:45], v[44:45], v[72:73] op_sel_hi:[1,0]
	s_nop 0
	v_pk_mul_f32 v[40:41], v[44:45], v[40:41]
	s_waitcnt vmcnt(6)
	v_pk_mul_f32 v[48:49], v[48:49], v[72:73] op_sel_hi:[1,0]
	s_waitcnt vmcnt(4)
	v_pk_mul_f32 v[44:45], v[56:57], v[72:73] op_sel_hi:[1,0]
	v_pk_mul_f32 v[42:43], v[48:49], v[42:43]
	v_pk_mul_f32 v[38:39], v[44:45], v[38:39]
	v_pk_mul_f32 v[44:45], v[52:53], v[72:73] op_sel_hi:[1,0]
	s_waitcnt vmcnt(2)
	v_pk_mul_f32 v[56:57], v[68:69], v[42:43]
	v_pk_mul_f32 v[34:35], v[44:45], v[34:35]
	v_pk_mul_f32 v[44:45], v[50:51], v[72:73] op_sel_hi:[1,0]
	s_nop 0
	v_pk_mul_f32 v[36:37], v[44:45], v[36:37]
	v_pk_mul_f32 v[44:45], v[46:47], v[72:73] op_sel_hi:[1,0]
	s_nop 0
	v_pk_mul_f32 v[32:33], v[44:45], v[32:33]
	v_pk_mul_f32 v[44:45], v[58:59], v[72:73] op_sel_hi:[1,0]
	s_nop 0
	v_pk_mul_f32 v[30:31], v[44:45], v[30:31]
	v_pk_mul_f32 v[44:45], v[54:55], v[72:73] op_sel_hi:[1,0]
	s_nop 0
	v_pk_mul_f32 v[28:29], v[44:45], v[28:29]
	v_mul_f32_e32 v44, v69, v42
	v_pk_fma_f32 v[44:45], v[68:69], v[42:43], v[44:45] op_sel:[1,0,0] op_sel_hi:[0,1,0]
	v_mul_f32_e32 v44, v71, v36
	v_pk_fma_f32 v[48:49], v[70:71], v[36:37], v[44:45] op_sel:[1,0,0] op_sel_hi:[0,1,0]
	v_mul_f32_e32 v44, v65, v40
	v_pk_fma_f32 v[46:47], v[64:65], v[40:41], v[44:45] op_sel:[1,0,0] op_sel_hi:[0,1,0]
	v_mul_f32_e32 v44, v67, v32
	v_pk_fma_f32 v[50:51], v[66:67], v[32:33], v[44:45] op_sel:[1,0,0] op_sel_hi:[0,1,0]
	s_waitcnt vmcnt(0)
	v_mul_f32_e32 v44, v23, v38
	v_pk_mul_f32 v[42:43], v[70:71], v[36:37]
	v_pk_mul_f32 v[36:37], v[64:65], v[40:41]
	v_pk_mul_f32 v[40:41], v[66:67], v[32:33]
	v_pk_mul_f32 v[32:33], v[22:23], v[38:39]
	v_pk_fma_f32 v[22:23], v[22:23], v[38:39], v[44:45] op_sel:[1,0,0] op_sel_hi:[0,1,0]
	v_mul_f32_e32 v22, v25, v30
	v_pk_mul_f32 v[38:39], v[24:25], v[30:31]
	v_pk_fma_f32 v[24:25], v[24:25], v[30:31], v[22:23] op_sel:[1,0,0] op_sel_hi:[0,1,0]
	v_mul_f32_e32 v22, v19, v34
	v_pk_fma_f32 v[52:53], v[18:19], v[34:35], v[22:23] op_sel:[1,0,0] op_sel_hi:[0,1,0]
	v_mul_f32_e32 v22, v21, v28
	v_pk_mul_f32 v[30:31], v[18:19], v[34:35]
	v_pk_mul_f32 v[18:19], v[20:21], v[28:29]
	v_pk_fma_f32 v[54:55], v[20:21], v[28:29], v[22:23] op_sel:[1,0,0] op_sel_hi:[0,1,0]
	v_sub_f32_e32 v44, v56, v57
	v_sub_f32_e32 v48, v42, v43
	v_sub_f32_e32 v46, v36, v37
	v_sub_f32_e32 v50, v40, v41
	v_sub_f32_e32 v22, v32, v33
	v_sub_f32_e32 v24, v38, v39
	v_sub_f32_e32 v52, v30, v31
	v_sub_f32_e32 v54, v18, v19
; DI float bf2f(short s) { return __uint_as_float(((unsigned)(unsigned short)s) << 16); }
; template <bool ROPE>
; DI void q_prep(bf16x8& q0, bf16x8& q1, const float* gq, int g, const float* rope, int t) {
;     float x[16]; float ss = 0.f;
; #pragma unroll
;     for (int e = 0; e < 8; ++e) { x[e] = bf2f(q0[e]); x[8 + e] = bf2f(q1[e]); ss += x[e] * x[e] + x[8 + e] * x[8 + e]; }
;     ss += __shfl_xor(ss, 16); ss += __shfl_xor(ss, 32);
;     const float rstd = rsqrtf(ss * (1.0f / 64.0f) + EPS);
;     const f32x4 ga = *(const f32x4*)(gq + 8 * g), gb = *(const f32x4*)(gq + 8 * g + 4), gc = *(const f32x4*)(gq + 32 + 8 * g), gd = *(const f32x4*)(gq + 32 + 8 * g + 4);
; #pragma unroll
;     for (int e = 0; e < 4; ++e) { x[e] *= rstd * ga[e]; x[4 + e] *= rstd * gb[e]; x[8 + e] *= rstd * gc[e]; x[12 + e] *= rstd * gd[e]; }
; DI float q_norm(bf16x8 q0, bf16x8 q1) {
;     float ss = 0.f;
; #pragma unroll
;     for (int e = 0; e < 8; ++e) { const float a = bf2f(q0[e]), b = bf2f(q1[e]); ss += a * a + b * b; }
;     ss += __shfl_xor(ss, 16); ss += __shfl_xor(ss, 32);
;     return sqrtf(ss);
; }
.LBB0_253:
	global_load_dwordx4 v[28:31], v[26:27], off offset:384
	global_load_dwordx4 v[56:59], v[26:27], off offset:448
	v_cvt_pk_bf16_f32 v22, v22, v23
	v_cvt_pk_bf16_f32 v18, v44, v45
	v_cvt_pk_bf16_f32 v23, v24, v25
	v_lshlrev_b32_e32 v27, 16, v22
	v_and_b32_e32 v33, 0xffff0000, v22
	v_cvt_pk_bf16_f32 v19, v48, v49
	v_lshlrev_b32_e32 v26, 16, v18
	v_and_b32_e32 v32, 0xffff0000, v18
	v_lshlrev_b32_e32 v35, 16, v23
	v_mul_f32_e32 v27, v27, v27
	v_mul_f32_e32 v33, v33, v33
	v_cvt_pk_bf16_f32 v24, v52, v53
	v_lshlrev_b32_e32 v34, 16, v19
	v_and_b32_e32 v37, 0xffff0000, v23
	v_mul_f32_e32 v35, v35, v35
	v_fmac_f32_e32 v27, v26, v26
	v_fmac_f32_e32 v33, v32, v32
	v_cvt_pk_bf16_f32 v20, v46, v47
	v_and_b32_e32 v36, 0xffff0000, v19
	v_lshlrev_b32_e32 v39, 16, v24
	v_mul_f32_e32 v37, v37, v37
	v_fmac_f32_e32 v35, v34, v34
	v_add_f32_e32 v26, v27, v33
	v_cvt_pk_bf16_f32 v25, v54, v55
	v_lshlrev_b32_e32 v38, 16, v20
	v_and_b32_e32 v41, 0xffff0000, v24
	v_mul_f32_e32 v39, v39, v39
	v_fmac_f32_e32 v37, v36, v36
	v_add_f32_e32 v26, v35, v26
	v_cvt_pk_bf16_f32 v21, v50, v51
	v_and_b32_e32 v40, 0xffff0000, v20
	v_lshlrev_b32_e32 v43, 16, v25
	v_mul_f32_e32 v41, v41, v41
	v_fmac_f32_e32 v39, v38, v38
	v_add_f32_e32 v26, v37, v26
	v_lshlrev_b32_e32 v42, 16, v21
	v_and_b32_e32 v45, 0xffff0000, v25
	v_mul_f32_e32 v43, v43, v43
	v_fmac_f32_e32 v41, v40, v40
	v_add_f32_e32 v26, v39, v26
	v_and_b32_e32 v44, 0xffff0000, v21
	v_mul_f32_e32 v45, v45, v45
	v_fmac_f32_e32 v43, v42, v42
	v_add_f32_e32 v26, v41, v26
	v_fmac_f32_e32 v45, v44, v44
	v_add_f32_e32 v26, v43, v26
	v_add_f32_e32 v32, v45, v26
	ds_bpermute_b32 v33, v120, v32
	v_mov_b32_e32 v66, v123
	s_mov_b64 s[74:75], -1
	v_lshlrev_b32_e32 v26, 3, v66
	s_waitcnt lgkmcnt(0)
	v_add_f32_e32 v64, v32, v33
	ds_bpermute_b32 v65, v121, v64
	s_and_b64 vcc, exec, s[4:5]
	v_ashrrev_i32_e32 v27, 31, v26
	s_waitcnt vmcnt(1)
	v_and_b32_e32 v39, 0xffff0000, v31
	v_lshlrev_b32_e32 v38, 16, v31
	s_waitcnt vmcnt(0)
	v_and_b32_e32 v35, 0xffff0000, v59
	v_lshlrev_b32_e32 v34, 16, v59
	v_and_b32_e32 v41, 0xffff0000, v58
	v_lshlrev_b32_e32 v40, 16, v58
	v_and_b32_e32 v37, 0xffff0000, v57
	v_lshlrev_b32_e32 v36, 16, v57
	v_and_b32_e32 v45, 0xffff0000, v56
	v_lshlrev_b32_e32 v44, 16, v56
	v_and_b32_e32 v47, 0xffff0000, v30
	v_lshlrev_b32_e32 v46, 16, v30
	v_and_b32_e32 v43, 0xffff0000, v29
	v_lshlrev_b32_e32 v42, 16, v29
	v_and_b32_e32 v49, 0xffff0000, v28
	v_lshlrev_b32_e32 v48, 16, v28
	s_cbranch_vccnz .LBB0_255
	v_lshl_add_u64 v[32:33], v[26:27], 2, s[6:7]
	global_load_dwordx4 v[28:31], v[32:33], off
	global_load_dwordx4 v[50:53], v[32:33], off offset:16
	global_load_dwordx4 v[54:57], v[32:33], off offset:128
	global_load_dwordx4 v[68:71], v[32:33], off offset:144
	v_pk_mul_f32 v[74:75], v[44:45], v[44:45]
	v_pk_mul_f32 v[72:73], v[36:37], v[36:37]
	v_pk_fma_f32 v[74:75], v[48:49], v[48:49], v[74:75]
	v_pk_fma_f32 v[72:73], v[42:43], v[42:43], v[72:73]
	v_add_f32_e32 v67, v74, v75
	v_pk_mul_f32 v[58:59], v[40:41], v[40:41]
	v_add_f32_e32 v67, v72, v67
	v_pk_fma_f32 v[58:59], v[46:47], v[46:47], v[58:59]
	v_add_f32_e32 v67, v73, v67
	v_pk_mul_f32 v[32:33], v[34:35], v[34:35]
	v_add_f32_e32 v58, v58, v67
	v_pk_fma_f32 v[32:33], v[38:39], v[38:39], v[32:33]
	v_add_f32_e32 v58, v59, v58
	v_add_f32_e32 v32, v32, v58
	v_add_f32_e32 v32, v33, v32
	ds_bpermute_b32 v33, v120, v32
	s_mov_b64 s[74:75], 0
	s_waitcnt lgkmcnt(0)
	v_add_f32_e32 v32, v32, v33
	ds_bpermute_b32 v33, v121, v32
	s_waitcnt lgkmcnt(0)
	v_add_f32_e32 v32, v32, v33
	v_fmamk_f32 v32, v32, 0x3c800000, v162
	v_mul_f32_e32 v33, 0x4b800000, v32
	v_cmp_gt_f32_e32 vcc, s27, v32
	s_nop 1
	v_cndmask_b32_e32 v32, v32, v33, vcc
	v_rsq_f32_e32 v32, v32
	s_nop 0
	v_mul_f32_e32 v33, 0x45800000, v32
	v_cndmask_b32_e32 v32, v32, v33, vcc
	v_mul_f32_e32 v32, 0x3e38aa3b, v32
	s_waitcnt vmcnt(3)
	v_pk_mul_f32 v[28:29], v[28:29], v[32:33] op_sel_hi:[1,0]
	s_waitcnt vmcnt(2)
	v_pk_mul_f32 v[58:59], v[50:51], v[32:33] op_sel_hi:[1,0]
	s_waitcnt vmcnt(1)
	v_pk_mul_f32 v[54:55], v[54:55], v[32:33] op_sel_hi:[1,0]
	s_waitcnt vmcnt(0)
	v_pk_mul_f32 v[68:69], v[68:69], v[32:33] op_sel_hi:[1,0]
	v_pk_mul_f32 v[72:73], v[30:31], v[32:33] op_sel_hi:[1,0]
	v_pk_mul_f32 v[74:75], v[52:53], v[32:33] op_sel_hi:[1,0]
	v_pk_mul_f32 v[76:77], v[56:57], v[32:33] op_sel_hi:[1,0]
	v_pk_mul_f32 v[70:71], v[70:71], v[32:33] op_sel_hi:[1,0]
	v_pk_mul_f32 v[50:51], v[28:29], v[48:49]
	v_pk_mul_f32 v[52:53], v[58:59], v[46:47]
	v_pk_mul_f32 v[30:31], v[54:55], v[44:45]
	v_pk_mul_f32 v[58:59], v[68:69], v[40:41]
	v_pk_mul_f32 v[54:55], v[72:73], v[42:43]
	v_pk_mul_f32 v[56:57], v[74:75], v[38:39]
	v_pk_mul_f32 v[32:33], v[76:77], v[36:37]
	v_pk_mul_f32 v[28:29], v[70:71], v[34:35]
; DI unsigned pk2(float lo, float hi) { f32x2 v = {lo, hi}; bf16x2_t b = __builtin_convertvector(v, bf16x2_t); return __builtin_bit_cast(unsigned, b); }
; template <bool ROPE>
; DI void q_prep(bf16x8& q0, bf16x8& q1, const float* gq, int g, const float* rope, int t) {
;     ...
;     if (ROPE) {
;         const float* rr = rope + ((t >> 6) * 16 + 4 * g) * 2; const float* rc = rope + ((t & 63) * 16 + 4 * g) * 2;
;         const f32x4 r0 = *(const f32x4*)rr, r1 = *(const f32x4*)(rr + 4), c0 = *(const f32x4*)rc, c1 = *(const f32x4*)(rc + 4);
;         const float cs[8] = {r0[0], r0[2], r1[0], r1[2], c0[0], c0[2], c1[0], c1[2]}, sn[8] = {r0[1], r0[3], r1[1], r1[3], c0[1], c0[3], c1[1], c1[3]};
; #pragma unroll
;         for (int i = 0; i < 8; ++i) { const float a = x[2 * i], b = x[2 * i + 1]; x[2 * i] = a * cs[i] - b * sn[i]; x[2 * i + 1] = a * sn[i] + b * cs[i]; }
;     }
;     u32x4 w0, w1; w0.x = pk2(x[0], x[1]); w0.y = pk2(x[2], x[3]); w0.z = pk2(x[4], x[5]); w0.w = pk2(x[6], x[7]); w1.x = pk2(x[8], x[9]); w1.y = pk2(x[10], x[11]); w1.z = pk2(x[12], x[13]); w1.w = pk2(x[14], x[15]);
;     q0 = __builtin_bit_cast(bf16x8, w0); q1 = __builtin_bit_cast(bf16x8, w1);
.LBB0_255:
	s_lshl_b32 s16, s11, 8
	s_mov_b32 s17, 0
	s_andn2_b64 vcc, exec, s[74:75]
	s_mov_b32 s18, 0
	s_cbranch_vccnz .LBB0_257
	v_lshl_add_u64 v[26:27], v[26:27], 2, s[6:7]
	global_load_dwordx4 v[50:53], v[26:27], off offset:16
	global_load_dwordx4 v[54:57], v[26:27], off
	global_load_dwordx4 v[68:71], v[26:27], off offset:144
	global_load_dwordx4 v[72:75], v[26:27], off offset:128
	s_add_i32 s36, s36, s83
	s_ashr_i32 s4, s36, 2
	s_and_b32 s4, s4, 0x7ffffff0
	v_lshlrev_b32_e32 v28, 2, v66
	v_add_lshl_u32 v26, v28, s4, 1
	v_add_lshl_u32 v28, v28, v130, 1
	v_ashrrev_i32_e32 v27, 31, v26
	v_ashrrev_i32_e32 v29, 31, v28
	v_lshl_add_u64 v[26:27], v[26:27], 2, s[8:9]
	v_lshl_add_u64 v[30:31], v[28:29], 2, s[8:9]
	global_load_dwordx4 v[76:79], v[26:27], off offset:16
	global_load_dwordx4 v[80:83], v[26:27], off
	s_nop 0
	global_load_dwordx4 v[26:29], v[30:31], off offset:16
	s_nop 0
	global_load_dwordx4 v[30:33], v[30:31], off
	v_pk_mul_f32 v[58:59], v[44:45], v[44:45]
	v_pk_mul_f32 v[66:67], v[36:37], v[36:37]
	v_pk_fma_f32 v[58:59], v[48:49], v[48:49], v[58:59]
	v_pk_fma_f32 v[66:67], v[42:43], v[42:43], v[66:67]
	v_add_f32_e32 v58, v58, v59
	v_pk_mul_f32 v[84:85], v[40:41], v[40:41]
	v_add_f32_e32 v58, v66, v58
	v_pk_fma_f32 v[84:85], v[46:47], v[46:47], v[84:85]
	v_add_f32_e32 v58, v67, v58
	v_pk_mul_f32 v[86:87], v[34:35], v[34:35]
	v_add_f32_e32 v58, v84, v58
	v_pk_fma_f32 v[86:87], v[38:39], v[38:39], v[86:87]
	v_add_f32_e32 v58, v85, v58
	v_add_f32_e32 v58, v86, v58
	v_add_f32_e32 v58, v87, v58
	ds_bpermute_b32 v59, v120, v58
	s_mov_b32 s18, 64
	s_waitcnt lgkmcnt(0)
	v_add_f32_e32 v58, v58, v59
	ds_bpermute_b32 v59, v121, v58
	s_waitcnt lgkmcnt(0)
	v_add_f32_e32 v58, v58, v59
	v_fmamk_f32 v58, v58, 0x3c800000, v162
	v_cmp_gt_f32_e32 vcc, s27, v58
	v_mul_f32_e32 v59, 0x4b800000, v58
	s_nop 0
	v_cndmask_b32_e32 v58, v58, v59, vcc
	v_rsq_f32_e32 v58, v58
	s_nop 0
	v_mul_f32_e32 v59, 0x45800000, v58
	v_cndmask_b32_e32 v58, v58, v59, vcc
	v_mul_f32_e32 v58, 0x3e38aa3b, v58
	s_waitcnt vmcnt(7)
	v_pk_mul_f32 v[50:51], v[50:51], v[58:59] op_sel_hi:[1,0]
	s_nop 0
	v_pk_mul_f32 v[46:47], v[50:51], v[46:47]
	s_waitcnt vmcnt(6)
	v_pk_mul_f32 v[54:55], v[54:55], v[58:59] op_sel_hi:[1,0]
	s_waitcnt vmcnt(4)
	v_pk_mul_f32 v[50:51], v[72:73], v[58:59] op_sel_hi:[1,0]
	v_pk_mul_f32 v[48:49], v[54:55], v[48:49]
	v_pk_mul_f32 v[44:45], v[50:51], v[44:45]
	v_pk_mul_f32 v[50:51], v[68:69], v[58:59] op_sel_hi:[1,0]
	s_waitcnt vmcnt(2)
	v_pk_mul_f32 v[66:67], v[80:81], v[48:49]
	v_pk_mul_f32 v[40:41], v[50:51], v[40:41]
	v_pk_mul_f32 v[50:51], v[56:57], v[58:59] op_sel_hi:[1,0]
	s_nop 0
	v_pk_mul_f32 v[42:43], v[50:51], v[42:43]
	v_pk_mul_f32 v[50:51], v[52:53], v[58:59] op_sel_hi:[1,0]
	s_nop 0
	v_pk_mul_f32 v[38:39], v[50:51], v[38:39]
	v_pk_mul_f32 v[50:51], v[74:75], v[58:59] op_sel_hi:[1,0]
	s_nop 0
	v_pk_mul_f32 v[36:37], v[50:51], v[36:37]
	v_pk_mul_f32 v[50:51], v[70:71], v[58:59] op_sel_hi:[1,0]
	s_nop 0
	v_pk_mul_f32 v[34:35], v[50:51], v[34:35]
	v_mul_f32_e32 v50, v81, v48
	v_pk_fma_f32 v[50:51], v[80:81], v[48:49], v[50:51] op_sel:[1,0,0] op_sel_hi:[0,1,0]
	v_mul_f32_e32 v50, v83, v42
	v_pk_fma_f32 v[54:55], v[82:83], v[42:43], v[50:51] op_sel:[1,0,0] op_sel_hi:[0,1,0]
	v_mul_f32_e32 v50, v77, v46
	v_pk_fma_f32 v[52:53], v[76:77], v[46:47], v[50:51] op_sel:[1,0,0] op_sel_hi:[0,1,0]
	v_mul_f32_e32 v50, v79, v38
	v_pk_fma_f32 v[56:57], v[78:79], v[38:39], v[50:51] op_sel:[1,0,0] op_sel_hi:[0,1,0]
	s_waitcnt vmcnt(0)
	v_mul_f32_e32 v50, v31, v44
	v_pk_mul_f32 v[48:49], v[82:83], v[42:43]
	v_pk_mul_f32 v[42:43], v[76:77], v[46:47]
	v_pk_mul_f32 v[46:47], v[78:79], v[38:39]
	v_pk_mul_f32 v[38:39], v[30:31], v[44:45]
	v_pk_fma_f32 v[30:31], v[30:31], v[44:45], v[50:51] op_sel:[1,0,0] op_sel_hi:[0,1,0]
	v_mul_f32_e32 v30, v33, v36
	v_pk_mul_f32 v[44:45], v[32:33], v[36:37]
	v_pk_fma_f32 v[32:33], v[32:33], v[36:37], v[30:31] op_sel:[1,0,0] op_sel_hi:[0,1,0]
	v_mul_f32_e32 v30, v27, v40
	v_pk_fma_f32 v[58:59], v[26:27], v[40:41], v[30:31] op_sel:[1,0,0] op_sel_hi:[0,1,0]
	v_mul_f32_e32 v30, v29, v34
	v_pk_mul_f32 v[36:37], v[26:27], v[40:41]
	v_pk_mul_f32 v[26:27], v[28:29], v[34:35]
	v_pk_fma_f32 v[28:29], v[28:29], v[34:35], v[30:31] op_sel:[1,0,0] op_sel_hi:[0,1,0]
	v_sub_f32_e32 v50, v66, v67
	v_sub_f32_e32 v54, v48, v49
	v_sub_f32_e32 v52, v42, v43
	v_sub_f32_e32 v56, v46, v47
	v_sub_f32_e32 v30, v38, v39
	v_sub_f32_e32 v32, v44, v45
	v_sub_f32_e32 v58, v36, v37
	v_sub_f32_e32 v28, v26, v27
; DI float bf2f(short s) { return __uint_as_float(((unsigned)(unsigned short)s) << 16); }
; DI float q_norm(bf16x8 q0, bf16x8 q1) {
;     float ss = 0.f;
; #pragma unroll
;     for (int e = 0; e < 8; ++e) { const float a = bf2f(q0[e]), b = bf2f(q1[e]); ss += a * a + b * b; }
;     ss += __shfl_xor(ss, 16); ss += __shfl_xor(ss, 32);
;     return sqrtf(ss);
; }
; DI void attn_odd_lds(Frame& F, const float* gk  , const float* gq  , bool with_ctx) {
;     ...
;         AT_ISSUE(0); AT_ISSUE(1); AT_ISSUE(2);
.LBB0_257:
	v_cvt_pk_bf16_f32 v46, v30, v31
	v_cvt_pk_bf16_f32 v42, v50, v51
	v_cvt_pk_bf16_f32 v49, v28, v29
	v_lshlrev_b32_e32 v29, 16, v46
	s_waitcnt lgkmcnt(0)
	v_add_f32_e32 v26, v64, v65
	v_lshlrev_b32_e32 v28, 16, v42
	v_mul_f32_e32 v29, v29, v29
	v_and_b32_e32 v30, 0xffff0000, v46
	v_mul_f32_e32 v27, 0x4f800000, v26
	v_cmp_gt_f32_e32 vcc, s48, v26
	v_fmac_f32_e32 v29, v28, v28
	v_and_b32_e32 v28, 0xffff0000, v42
	v_mul_f32_e32 v30, v30, v30
	v_cndmask_b32_e32 v27, v26, v27, vcc
	v_cvt_pk_bf16_f32 v47, v32, v33
	v_fmac_f32_e32 v30, v28, v28
	v_sqrt_f32_e32 v34, v27
	v_cvt_pk_bf16_f32 v43, v54, v55
	v_add_f32_e32 v28, v29, v30
	v_lshlrev_b32_e32 v30, 16, v47
	v_lshlrev_b32_e32 v29, 16, v43
	v_mul_f32_e32 v30, v30, v30
	v_fmac_f32_e32 v30, v29, v29
	v_add_f32_e32 v28, v30, v28
	v_and_b32_e32 v30, 0xffff0000, v47
	v_add_u32_e32 v35, -1, v34
	v_and_b32_e32 v29, 0xffff0000, v43
	v_mul_f32_e32 v30, v30, v30
	v_fma_f32 v36, -v35, v34, v27
	v_cvt_pk_bf16_f32 v48, v58, v59
	v_fmac_f32_e32 v30, v29, v29
	v_cmp_ge_f32_e64 s[4:5], 0, v36
	v_add_u32_e32 v36, 1, v34
	v_cvt_pk_bf16_f32 v44, v52, v53
	v_add_f32_e32 v28, v30, v28
	v_lshlrev_b32_e32 v30, 16, v48
	v_cndmask_b32_e64 v35, v34, v35, s[4:5]
	v_fma_f32 v34, -v36, v34, v27
	v_lshlrev_b32_e32 v29, 16, v44
	v_mul_f32_e32 v30, v30, v30
	v_cmp_lt_f32_e64 s[4:5], 0, v34
	v_fmac_f32_e32 v30, v29, v29
	v_add_f32_e32 v28, v30, v28
	v_cndmask_b32_e64 v34, v35, v36, s[4:5]
	v_add_f32_e32 v36, v62, v63
	v_and_b32_e32 v30, 0xffff0000, v48
	v_mul_f32_e32 v37, 0x4f800000, v36
	v_cmp_gt_f32_e64 s[4:5], s48, v36
	v_and_b32_e32 v29, 0xffff0000, v44
	v_mul_f32_e32 v30, v30, v30
	v_cndmask_b32_e64 v36, v36, v37, s[4:5]
	v_fmac_f32_e32 v30, v29, v29
	v_sqrt_f32_e32 v37, v36
	v_cvt_pk_bf16_f32 v45, v56, v57
	v_add_f32_e32 v28, v30, v28
	v_lshlrev_b32_e32 v30, 16, v49
	v_lshlrev_b32_e32 v29, 16, v45
	v_mul_f32_e32 v30, v30, v30
	v_mul_f32_e32 v35, 0x37800000, v34
	v_fmac_f32_e32 v30, v29, v29
	v_cndmask_b32_e32 v34, v34, v35, vcc
	v_cmp_class_f32_e32 vcc, v27, v187
	v_add_f32_e32 v28, v30, v28
	v_and_b32_e32 v30, 0xffff0000, v49
	v_cndmask_b32_e32 v27, v34, v27, vcc
	v_add_u32_e32 v34, -1, v37
	v_and_b32_e32 v29, 0xffff0000, v45
	v_mul_f32_e32 v30, v30, v30
	v_fma_f32 v35, -v34, v37, v36
	v_fmac_f32_e32 v30, v29, v29
	v_cmp_ge_f32_e32 vcc, 0, v35
	v_add_u32_e32 v35, 1, v37
	v_add_f32_e32 v28, v30, v28
	v_cndmask_b32_e32 v34, v37, v34, vcc
	v_fma_f32 v37, -v35, v37, v36
	ds_bpermute_b32 v29, v120, v28
	v_cmp_lt_f32_e32 vcc, 0, v37
	v_add_f32_e32 v37, v60, v61
	v_mul_f32_e32 v38, 0x4f800000, v37
	v_cndmask_b32_e32 v34, v34, v35, vcc
	v_cmp_gt_f32_e32 vcc, s48, v37
	s_waitcnt lgkmcnt(0)
	v_add_f32_e32 v28, v28, v29
	ds_bpermute_b32 v29, v121, v28
	v_cndmask_b32_e32 v37, v37, v38, vcc
	v_sqrt_f32_e32 v38, v37
	v_mul_f32_e32 v35, 0x37800000, v34
	v_cndmask_b32_e64 v34, v34, v35, s[4:5]
	v_cmp_class_f32_e64 s[4:5], v36, v187
	v_add_u32_e32 v35, -1, v38
	v_fma_f32 v30, -v35, v38, v37
	v_add_u32_e32 v31, 1, v38
	v_cndmask_b32_e64 v34, v34, v36, s[4:5]
	v_cmp_ge_f32_e64 s[4:5], 0, v30
	v_fma_f32 v32, -v31, v38, v37
	s_waitcnt lgkmcnt(0)
	v_add_f32_e32 v28, v28, v29
	v_cndmask_b32_e64 v30, v38, v35, s[4:5]
	v_cmp_lt_f32_e64 s[4:5], 0, v32
	v_mul_f32_e32 v29, 0x4f800000, v28
	s_ashr_i32 s73, s72, 31
	v_cndmask_b32_e64 v30, v30, v31, s[4:5]
	v_cmp_gt_f32_e64 s[4:5], s48, v28
	v_mul_f32_e32 v31, 0x37800000, v30
	v_cndmask_b32_e32 v30, v30, v31, vcc
	v_cndmask_b32_e64 v28, v28, v29, s[4:5]
	v_sqrt_f32_e32 v29, v28
	v_cmp_class_f32_e32 vcc, v37, v187
	v_mov_b32_e32 v26, 0
	v_mul_f32_e64 v133, v126, -v34
	v_mov_b32_e32 v232, v133
	v_mov_b32_e32 v233, v133
	v_mov_b32_e32 v234, v133
	v_mov_b32_e32 v235, v133
	v_add_u32_e32 v31, -1, v29
	v_fma_f32 v32, -v31, v29, v28
	v_cndmask_b32_e32 v30, v30, v37, vcc
	v_cmp_ge_f32_e32 vcc, 0, v32
	v_add_u32_e32 v32, 1, v29
	v_mul_f32_e64 v132, v126, -v30
	v_mov_b32_e32 v228, v132
	v_mov_b32_e32 v229, v132
	v_mov_b32_e32 v230, v132
	v_mov_b32_e32 v231, v132
	v_cndmask_b32_e32 v31, v29, v31, vcc
	v_fma_f32 v29, -v32, v29, v28
	v_cmp_lt_f32_e32 vcc, 0, v29
	v_mul_f32_e64 v134, v126, -v27
	v_mov_b32_e32 v236, v134
	v_mov_b32_e32 v237, v134
	v_mov_b32_e32 v238, v134
	v_mov_b32_e32 v239, v134
	v_mov_b32_e32 v27, v26
	v_cndmask_b32_e32 v29, v31, v32, vcc
	v_mul_f32_e32 v31, 0x37800000, v29
	v_cndmask_b32_e64 v29, v29, v31, s[4:5]
	s_mul_i32 s5, s72, 0xe00
	s_mul_hi_i32 s4, s72, 0xe00
	s_add_u32 s5, s62, s5
	s_addc_u32 s4, s63, s4
	s_add_u32 s12, s5, 0x400
	s_addc_u32 s13, s4, 0
	s_lshl_b32 s20, s11, 7
	s_add_u32 s5, s5, s20
	s_addc_u32 s4, s4, 0
	s_add_u32 s19, s5, 0x400
	s_addc_u32 s22, s4, 0
	s_mul_i32 s11, s11, 0x880000
	s_add_u32 s29, s42, s11
	s_addc_u32 s30, s43, 0
	s_lshl_b64 s[4:5], s[72:73], 1
	s_add_u32 s11, s29, s4
	s_addc_u32 s26, s30, s5
	s_mul_hi_i32 s4, s10, 0xe00
	s_mulk_i32 s10, 0xe00
	s_add_u32 s5, s62, s10
	s_addc_u32 s4, s63, s4
	s_add_u32 s34, s5, 0x400
	s_addc_u32 s39, s4, 0
	s_add_u32 s5, s5, s20
	s_addc_u32 s4, s4, 0
	s_add_u32 s10, s5, 0x400
	s_addc_u32 s28, s4, 0
	s_ashr_i32 s71, s70, 31
	s_lshl_b64 s[4:5], s[70:71], 1
	s_add_u32 s4, s29, s4
	s_addc_u32 s5, s30, s5
	s_add_u32 s30, s4, 0x20000
	s_addc_u32 s31, s5, 0
	s_or_b32 s33, s18, 4
	s_and_b64 s[4:5], s[68:69], exec
	s_cselect_b32 s4, s19, s10
	s_cselect_b32 s5, s22, s28
	s_cselect_b32 s37, s26, s31
	s_cselect_b32 s36, s11, s30
	s_mov_b32 s29, m0
	s_mov_b32 m0, s80
	s_nop 0
	global_load_lds_dwordx4 v124, s[4:5]
	s_mov_b32 m0, s29
	s_add_i32 s4, s80, 0x2400
	s_mov_b32 s5, m0
	s_mov_b32 m0, s4
	s_nop 0
	global_load_lds_dwordx4 v125, s[36:37]
	s_mov_b32 m0, s5
	s_and_b64 s[4:5], s[68:69], exec
	s_cselect_b32 s5, s12, s34
; #define LAS __attribute__((address_space(3)))
; DI unsigned pk2(float lo, float hi) { f32x2 v = {lo, hi}; bf16x2_t b = __builtin_convertvector(v, bf16x2_t); return __builtin_bit_cast(unsigned, b); }
; DI void attn_group4(f32x4 (&o)[4][4], const float (&mref)[4], float (&ls)[4], const bf16x8 (&q)[4][2], bf16x8 k00, bf16x8 k01, bf16x8 k10, bf16x8 k11,
;                     bf16x8 v0, bf16x8 v1, bf16x8 v2, bf16x8 v3) {
;     const f32x4 z = {0.f, 0.f, 0.f, 0.f};
;     constexpr float C = 0.125f * LOG2E;
;     f32x4 s0[4], s1[4];
;     __builtin_amdgcn_s_setprio(1);
; #pragma unroll
;     for (int h = 0; h < 4; ++h) { s0[h] = MFMA16(k00, q[h][0], z); s1[h] = MFMA16(k10, q[h][0], z); }
; #pragma unroll
;     for (int h = 0; h < 4; ++h) { s0[h] = MFMA16(k01, q[h][1], s0[h]); s1[h] = MFMA16(k11, q[h][1], s1[h]); }
;     __builtin_amdgcn_s_setprio(0);
;     bf16x8 pb[4];
; #pragma unroll
;     for (int h = 0; h < 4; ++h) {
;         f32x4 p0, p1;
; #pragma unroll
;         for (int e = 0; e < 4; ++e) { p0[e] = __builtin_amdgcn_exp2f(__builtin_fmaf(s0[h][e], C, -mref[h])); p1[e] = __builtin_amdgcn_exp2f(__builtin_fmaf(s1[h][e], C, -mref[h])); }
;         ls[h] += ((p0[0] + p0[1]) + (p0[2] + p0[3])) + ((p1[0] + p1[1]) + (p1[2] + p1[3]));
;         u32x4 pw; pw.x = pk2(p0[0], p0[1]); pw.y = pk2(p0[2], p0[3]); pw.z = pk2(p1[0], p1[1]); pw.w = pk2(p1[2], p1[3]);
;         pb[h] = __builtin_bit_cast(bf16x8, pw);
;     }
; DI void attn_odd_lds(Frame& F, const float* gk  , const float* gq  , bool with_ctx) {
;     ...
;         AT_ISSUE(0); AT_ISSUE(1); AT_ISSUE(2);
; #pragma unroll 1
;         for (int s = 0; s < n; ++s) {
;             if (s + 2 < n) AT_WAIT_BAR(4); else if (s + 1 < n) AT_WAIT_BAR(2); else AT_WAIT_BAR(0);
;             if (s + 3 < n) AT_ISSUE(s + 3);
;             const LAS unsigned char* sk = F.lds + (s & 3) * AT_SLOT + bk; const LAS unsigned char* sv = F.lds + (s & 3) * AT_SLOT + bv;
; #pragma unroll
;             for (int hf = 0; hf < 2; ++hf) {
;                 const bf16x8 k00 = LDS_K(sk, hf * 32, 0, 0), k01 = LDS_K(sk, hf * 32, 0, 1), k10 = LDS_K(sk, hf * 32, 1, 0), k11 = LDS_K(sk, hf * 32, 1, 1);
;                 const bf16x8 v0 = LDS_V(sv, 0, hf * 4), v1 = LDS_V(sv, 1, hf * 4), v2 = LDS_V(sv, 2, hf * 4), v3 = LDS_V(sv, 3, hf * 4);
;                 attn_group4(o, mx, ls, q, k00, k01, k10, k11, v0, v1, v2, v3);
	s_cselect_b32 s4, s13, s39
	s_add_u32 s12, s5, s20
	s_addc_u32 s13, s4, 0
	s_add_u32 s4, s12, 0x38000
	s_addc_u32 s5, s13, 0
	s_add_u32 s40, s36, 0x80
	s_addc_u32 s41, s37, 0
	s_mov_b32 s20, m0
	s_mov_b32 m0, s81
	s_nop 0
	global_load_lds_dwordx4 v124, s[4:5]
	s_mov_b32 m0, s20
	s_add_i32 s4, s81, 0x2400
	s_mov_b32 s5, m0
	s_mov_b32 m0, s4
	s_nop 0
	global_load_lds_dwordx4 v125, s[40:41]
	s_mov_b32 m0, s5
	s_add_u32 s4, s12, 0x70000
	s_addc_u32 s5, s13, 0
	s_add_u32 s36, s36, 0x100
	s_mov_b32 s12, m0
	s_mov_b32 m0, s82
	s_nop 0
	global_load_lds_dwordx4 v124, s[4:5]
	s_mov_b32 m0, s12
	v_cmp_class_f32_e32 vcc, v28, v187
	s_addc_u32 s37, s37, 0
	s_add_i32 s4, s82, 0x2400
	s_mov_b32 s5, m0
	s_mov_b32 m0, s4
	s_nop 0
	global_load_lds_dwordx4 v125, s[36:37]
	s_mov_b32 m0, s5
	v_cndmask_b32_e32 v28, v29, v28, vcc
	s_or_b32 s34, s18, 2
	s_or_b32 s36, s18, 3
	v_mul_f32_e64 v135, v126, -v28
	v_mov_b32_e32 v240, v135
	v_mov_b32_e32 v241, v135
	v_mov_b32_e32 v242, v135
	v_mov_b32_e32 v243, v135
	s_add_i32 s37, s18, 4
	s_movk_i32 s39, 0xc0
	v_mov_b32_e32 v28, v26
	v_mov_b32_e32 v29, v26
	v_mov_b32_e32 v30, v26
	v_mov_b32_e32 v31, v26
	v_mov_b32_e32 v32, v26
	v_mov_b32_e32 v33, v26
	v_mov_b32_e32 v34, v26
	v_mov_b32_e32 v35, v26
	v_mov_b32_e32 v36, v26
	v_mov_b32_e32 v37, v26
	v_mov_b32_e32 v38, v26
	v_mov_b32_e32 v39, v26
	v_mov_b32_e32 v40, v26
	v_mov_b32_e32 v41, v26
	v_mov_b32_e32 v50, v26
	v_mov_b32_e32 v51, v26
	v_mov_b32_e32 v52, v26
	v_mov_b32_e32 v53, v26
	v_mov_b32_e32 v54, v26
	v_mov_b32_e32 v55, v26
	v_mov_b32_e32 v56, v26
	v_mov_b32_e32 v57, v26
	v_mov_b32_e32 v58, v26
	v_mov_b32_e32 v59, v26
	v_mov_b32_e32 v60, v26
	v_mov_b32_e32 v61, v26
	v_mov_b32_e32 v62, v26
	v_mov_b32_e32 v63, v26
	v_mov_b32_e32 v64, v26
	v_mov_b32_e32 v65, v26
	v_mov_b32_e32 v66, v26
	v_mov_b32_e32 v67, v26
	v_mov_b32_e32 v68, v26
	v_mov_b32_e32 v69, v26
	v_mov_b32_e32 v70, v26
	v_mov_b32_e32 v71, v26
	v_mov_b32_e32 v72, v26
	v_mov_b32_e32 v73, v26
	v_mov_b32_e32 v74, v26
	v_mov_b32_e32 v75, v26
	v_mov_b32_e32 v76, v26
	v_mov_b32_e32 v77, v26
	v_mov_b32_e32 v78, v26
	v_mov_b32_e32 v79, v26
	v_mov_b32_e32 v80, v26
	v_mov_b32_e32 v81, v26
	v_mov_b32_e32 v82, v26
	v_mov_b32_e32 v83, v26
	v_mov_b32_e32 v84, v26
	v_mov_b32_e32 v85, v26
	v_mov_b32_e32 v86, v26
	v_mov_b32_e32 v87, v26
	v_mov_b32_e32 v88, v26
	v_mov_b32_e32 v89, v26
	v_mov_b32_e32 v90, v26
	v_mov_b32_e32 v91, v26
	v_mov_b32_e32 v92, v26
	v_mov_b32_e32 v93, v26
	v_mov_b32_e32 v94, v26
	v_mov_b32_e32 v95, v26
	v_mov_b32_e32 v96, v26
	v_mov_b32_e32 v97, v26
	v_mov_b32_e32 v104, v26
	v_mov_b32_e32 v105, v26
	v_mov_b32_e32 v106, v26
	v_mov_b32_e32 v107, v26
	s_branch .LBB0_259
.LBB0_258:
	s_and_b32 s4, s17, 3
	s_mulk_i32 s4, 0x4800
	v_add_u32_e32 v98, s4, v131
	v_add_u32_e32 v165, v98, v127
	v_add3_u32 v168, v98, v128, v129
	ds_read_b128 v[98:101], v165
	ds_read_b128 v[108:111], v165 offset:512
	ds_read_b128 v[112:115], v165 offset:2304
	ds_read_b128 v[116:119], v165 offset:2816
	v_add_u32_e32 v195, 0x2000, v168
	v_add_u32_e32 v140, 0x2800, v168
	v_add_u32_e32 v144, 0x3000, v168
	v_add_u32_e32 v148, 0x3c00, v168
	ds_read2_b64 v[136:139], v195 offset0:128 offset1:160
	ds_read2_b64 v[140:143], v140 offset0:160 offset1:192
	ds_read2_b64 v[144:147], v144 offset0:192 offset1:224
	ds_read2_b64 v[148:151], v148 offset0:96 offset1:128
	s_setprio 1
	s_waitcnt lgkmcnt(7)
	v_mfma_f32_16x16x32_bf16 v[152:155], v[98:101], v[2:5], v[228:231]
	s_waitcnt lgkmcnt(5)
	v_mfma_f32_16x16x32_bf16 v[156:159], v[112:115], v[2:5], v[228:231]
	v_mfma_f32_16x16x32_bf16 v[170:173], v[98:101], v[10:13], v[232:235]
	v_mfma_f32_16x16x32_bf16 v[174:177], v[112:115], v[10:13], v[232:235]
	v_mfma_f32_16x16x32_bf16 v[188:191], v[98:101], v[18:21], v[236:239]
	v_mfma_f32_16x16x32_bf16 v[196:199], v[112:115], v[18:21], v[236:239]
	v_mfma_f32_16x16x32_bf16 v[98:101], v[98:101], v[42:45], v[240:243]
	v_mfma_f32_16x16x32_bf16 v[112:115], v[112:115], v[42:45], v[240:243]
	v_mfma_f32_16x16x32_bf16 v[152:155], v[108:111], v[6:9], v[152:155]
	s_waitcnt lgkmcnt(4)
	v_mfma_f32_16x16x32_bf16 v[156:159], v[116:119], v[6:9], v[156:159]
	v_mfma_f32_16x16x32_bf16 v[170:173], v[108:111], v[14:17], v[170:173]
	v_mfma_f32_16x16x32_bf16 v[174:177], v[116:119], v[14:17], v[174:177]
	v_mfma_f32_16x16x32_bf16 v[188:191], v[108:111], v[22:25], v[188:191]
	v_mfma_f32_16x16x32_bf16 v[196:199], v[116:119], v[22:25], v[196:199]
	v_mfma_f32_16x16x32_bf16 v[98:101], v[108:111], v[46:49], v[98:101]
	v_mfma_f32_16x16x32_bf16 v[200:203], v[116:119], v[46:49], v[112:115]
	s_setprio 0
	v_exp_f32_e32 v161, v152
	v_exp_f32_e32 v167, v156
	v_exp_f32_e32 v179, v153
	v_exp_f32_e32 v185, v157
	v_exp_f32_e32 v213, v154
	v_exp_f32_e32 v215, v158
	v_exp_f32_e32 v217, v155
	v_exp_f32_e32 v219, v159
	v_exp_f32_e32 v160, v170
	v_exp_f32_e32 v166, v174
	v_exp_f32_e32 v178, v171
	v_exp_f32_e32 v184, v175
	v_exp_f32_e32 v212, v172
	v_exp_f32_e32 v214, v176
	v_exp_f32_e32 v216, v173
	v_exp_f32_e32 v218, v177
	v_exp_f32_e32 v117, v188
	v_exp_f32_e32 v109, v196
	v_exp_f32_e32 v221, v189
	v_exp_f32_e32 v113, v197
	v_exp_f32_e32 v119, v190
	v_exp_f32_e32 v111, v198
	v_exp_f32_e32 v223, v191
	v_exp_f32_e32 v116, v98
	v_exp_f32_e32 v115, v199
	v_exp_f32_e32 v108, v200
	v_exp_f32_e32 v220, v99
	v_exp_f32_e32 v112, v201
	v_exp_f32_e32 v118, v100
	v_exp_f32_e32 v110, v202
	v_exp_f32_e32 v222, v101
	v_exp_f32_e32 v114, v203
	v_cvt_pk_bf16_f32 v152, v161, v179
	v_cvt_pk_bf16_f32 v153, v213, v217
	v_cvt_pk_bf16_f32 v154, v167, v185
	v_cvt_pk_bf16_f32 v155, v215, v219
	v_cvt_pk_bf16_f32 v156, v160, v178
	v_cvt_pk_bf16_f32 v157, v212, v216
	v_cvt_pk_bf16_f32 v158, v166, v184
	v_cvt_pk_bf16_f32 v159, v214, v218
	v_cvt_pk_bf16_f32 v170, v117, v221
	v_cvt_pk_bf16_f32 v171, v119, v223
	v_cvt_pk_bf16_f32 v172, v109, v113
	v_cvt_pk_bf16_f32 v173, v111, v115
	v_cvt_pk_bf16_f32 v98, v116, v220
	v_cvt_pk_bf16_f32 v99, v118, v222
	v_cvt_pk_bf16_f32 v100, v108, v112
	v_cvt_pk_bf16_f32 v101, v110, v114
	s_setprio 1
	s_waitcnt lgkmcnt(3)
; #define MFMA16(a, b, c) __builtin_amdgcn_mfma_f32_16x16x32_bf16((a), (b), (c), 0, 0, 0)
; DI void attn_group4(f32x4 (&o)[4][4], const float (&mref)[4], float (&ls)[4], const bf16x8 (&q)[4][2], bf16x8 k00, bf16x8 k01, bf16x8 k10, bf16x8 k11,
;                     bf16x8 v0, bf16x8 v1, bf16x8 v2, bf16x8 v3) {
;     const f32x4 z = {0.f, 0.f, 0.f, 0.f};
;     constexpr float C = 0.125f * LOG2E;
;     f32x4 s0[4], s1[4];
;     __builtin_amdgcn_s_setprio(1);
; #pragma unroll
;     for (int h = 0; h < 4; ++h) { s0[h] = MFMA16(k00, q[h][0], z); s1[h] = MFMA16(k10, q[h][0], z); }
; #pragma unroll
;     for (int h = 0; h < 4; ++h) { s0[h] = MFMA16(k01, q[h][1], s0[h]); s1[h] = MFMA16(k11, q[h][1], s1[h]); }
;     ...
;     __builtin_amdgcn_s_setprio(1);
; #pragma unroll
;     for (int h = 0; h < 4; ++h) { o[h][0] = MFMA16(v0, pb[h], o[h][0]); o[h][1] = MFMA16(v1, pb[h], o[h][1]); o[h][2] = MFMA16(v2, pb[h], o[h][2]); o[h][3] = MFMA16(v3, pb[h], o[h][3]); }
;     __builtin_amdgcn_s_setprio(0);
	v_mfma_f32_16x16x32_bf16 v[94:97], v[136:139], v[152:155], v[94:97]
	s_waitcnt lgkmcnt(2)
	v_mfma_f32_16x16x32_bf16 v[90:93], v[140:143], v[152:155], v[90:93]
	s_waitcnt lgkmcnt(1)
	v_mfma_f32_16x16x32_bf16 v[86:89], v[144:147], v[152:155], v[86:89]
	s_waitcnt lgkmcnt(0)
	v_mfma_f32_16x16x32_bf16 v[82:85], v[148:151], v[152:155], v[82:85]
	v_mfma_f32_16x16x32_bf16 v[78:81], v[136:139], v[156:159], v[78:81]
	v_mfma_f32_16x16x32_bf16 v[74:77], v[140:143], v[156:159], v[74:77]
	v_mfma_f32_16x16x32_bf16 v[70:73], v[144:147], v[156:159], v[70:73]
	v_mfma_f32_16x16x32_bf16 v[66:69], v[148:151], v[156:159], v[66:69]
	v_mfma_f32_16x16x32_bf16 v[62:65], v[136:139], v[170:173], v[62:65]
	v_mfma_f32_16x16x32_bf16 v[58:61], v[140:143], v[170:173], v[58:61]
	v_mfma_f32_16x16x32_bf16 v[54:57], v[144:147], v[170:173], v[54:57]
	v_mfma_f32_16x16x32_bf16 v[50:53], v[148:151], v[170:173], v[50:53]
	v_mfma_f32_16x16x32_bf16 v[38:41], v[136:139], v[98:101], v[38:41]
	v_mfma_f32_16x16x32_bf16 v[34:37], v[140:143], v[98:101], v[34:37]
	v_mfma_f32_16x16x32_bf16 v[30:33], v[144:147], v[98:101], v[30:33]
	v_mfma_f32_16x16x32_bf16 v[26:29], v[148:151], v[98:101], v[26:29]
	s_setprio 0
	ds_read_b128 v[136:139], v165 offset:4608
	ds_read_b128 v[140:143], v165 offset:5120
	ds_read_b128 v[144:147], v165 offset:6912
	ds_read_b128 v[148:151], v165 offset:7424
	ds_read2_b64 v[98:101], v195 offset0:192 offset1:224
	v_add_u32_e32 v152, 0x2c00, v168
	v_add_u32_e32 v156, 0x3800, v168
	v_add_u32_e32 v165, 0x4000, v168
	ds_read2_b64 v[152:155], v152 offset0:96 offset1:128
	ds_read2_b64 v[156:159], v156 offset1:32
	ds_read2_b64 v[170:173], v165 offset0:32 offset1:64
	s_setprio 1
	s_waitcnt lgkmcnt(7)
	v_mfma_f32_16x16x32_bf16 v[174:177], v[136:139], v[2:5], v[228:231]
	s_waitcnt lgkmcnt(5)
	v_mfma_f32_16x16x32_bf16 v[188:191], v[144:147], v[2:5], v[228:231]
	v_mfma_f32_16x16x32_bf16 v[196:199], v[136:139], v[10:13], v[232:235]
	v_mfma_f32_16x16x32_bf16 v[200:203], v[144:147], v[10:13], v[232:235]
	v_mfma_f32_16x16x32_bf16 v[204:207], v[136:139], v[18:21], v[236:239]
	v_mfma_f32_16x16x32_bf16 v[208:211], v[144:147], v[18:21], v[236:239]
	v_mfma_f32_16x16x32_bf16 v[136:139], v[136:139], v[42:45], v[240:243]
	v_mfma_f32_16x16x32_bf16 v[144:147], v[144:147], v[42:45], v[240:243]
	v_mfma_f32_16x16x32_bf16 v[174:177], v[140:143], v[6:9], v[174:177]
	s_waitcnt lgkmcnt(4)
; #define LAS __attribute__((address_space(3)))
; DI unsigned pk2(float lo, float hi) { f32x2 v = {lo, hi}; bf16x2_t b = __builtin_convertvector(v, bf16x2_t); return __builtin_bit_cast(unsigned, b); }
; DI void attn_group4(f32x4 (&o)[4][4], const float (&mref)[4], float (&ls)[4], const bf16x8 (&q)[4][2], bf16x8 k00, bf16x8 k01, bf16x8 k10, bf16x8 k11,
;                     bf16x8 v0, bf16x8 v1, bf16x8 v2, bf16x8 v3) {
;     ...
;     for (int h = 0; h < 4; ++h) { s0[h] = MFMA16(k01, q[h][1], s0[h]); s1[h] = MFMA16(k11, q[h][1], s1[h]); }
;     __builtin_amdgcn_s_setprio(0);
;     bf16x8 pb[4];
; #pragma unroll
;     for (int h = 0; h < 4; ++h) {
;         f32x4 p0, p1;
; #pragma unroll
;         for (int e = 0; e < 4; ++e) { p0[e] = __builtin_amdgcn_exp2f(__builtin_fmaf(s0[h][e], C, -mref[h])); p1[e] = __builtin_amdgcn_exp2f(__builtin_fmaf(s1[h][e], C, -mref[h])); }
;         ls[h] += ((p0[0] + p0[1]) + (p0[2] + p0[3])) + ((p1[0] + p1[1]) + (p1[2] + p1[3]));
;         u32x4 pw; pw.x = pk2(p0[0], p0[1]); pw.y = pk2(p0[2], p0[3]); pw.z = pk2(p1[0], p1[1]); pw.w = pk2(p1[2], p1[3]);
;         pb[h] = __builtin_bit_cast(bf16x8, pw);
;     }
;     __builtin_amdgcn_s_setprio(1);
; #pragma unroll
;     for (int h = 0; h < 4; ++h) { o[h][0] = MFMA16(v0, pb[h], o[h][0]); o[h][1] = MFMA16(v1, pb[h], o[h][1]); o[h][2] = MFMA16(v2, pb[h], o[h][2]); o[h][3] = MFMA16(v3, pb[h], o[h][3]); }
;     __builtin_amdgcn_s_setprio(0);
; DI void attn_odd_lds(Frame& F, const float* gk  , const float* gq  , bool with_ctx) {
;     ...
; #pragma unroll 1
;         for (int s = 0; s < n; ++s) {
;             if (s + 2 < n) AT_WAIT_BAR(4); else if (s + 1 < n) AT_WAIT_BAR(2); else AT_WAIT_BAR(0);
;             if (s + 3 < n) AT_ISSUE(s + 3);
;             const LAS unsigned char* sk = F.lds + (s & 3) * AT_SLOT + bk; const LAS unsigned char* sv = F.lds + (s & 3) * AT_SLOT + bv;
; #pragma unroll
;             for (int hf = 0; hf < 2; ++hf) {
;                 const bf16x8 k00 = LDS_K(sk, hf * 32, 0, 0), k01 = LDS_K(sk, hf * 32, 0, 1), k10 = LDS_K(sk, hf * 32, 1, 0), k11 = LDS_K(sk, hf * 32, 1, 1);
;                 const bf16x8 v0 = LDS_V(sv, 0, hf * 4), v1 = LDS_V(sv, 1, hf * 4), v2 = LDS_V(sv, 2, hf * 4), v3 = LDS_V(sv, 3, hf * 4);
;                 attn_group4(o, mx, ls, q, k00, k01, k10, k11, v0, v1, v2, v3);
;             }
;         }
	v_mfma_f32_16x16x32_bf16 v[188:191], v[148:151], v[6:9], v[188:191]
	v_mfma_f32_16x16x32_bf16 v[196:199], v[140:143], v[14:17], v[196:199]
	v_mfma_f32_16x16x32_bf16 v[200:203], v[148:151], v[14:17], v[200:203]
	v_mfma_f32_16x16x32_bf16 v[204:207], v[140:143], v[22:25], v[204:207]
	v_mfma_f32_16x16x32_bf16 v[208:211], v[148:151], v[22:25], v[208:211]
	v_mfma_f32_16x16x32_bf16 v[136:139], v[140:143], v[46:49], v[136:139]
	v_mfma_f32_16x16x32_bf16 v[140:143], v[148:151], v[46:49], v[144:147]
	s_setprio 0
	s_nop 1
	v_exp_f32_e32 v149, v174
	v_exp_f32_e32 v151, v188
	v_exp_f32_e32 v175, v175
	v_exp_f32_e32 v174, v197
	v_exp_f32_e32 v189, v189
	v_exp_f32_e32 v188, v201
	v_exp_f32_e32 v225, v176
	v_exp_f32_e32 v224, v198
	v_exp_f32_e32 v227, v190
	v_exp_f32_e32 v226, v202
	v_exp_f32_e32 v177, v177
	v_exp_f32_e32 v148, v196
	v_exp_f32_e32 v176, v199
	v_pk_add_f32 v[160:161], v[160:161], v[178:179]
	v_pk_add_f32 v[178:179], v[212:213], v[216:217]
	v_exp_f32_e32 v191, v191
	v_exp_f32_e32 v150, v200
	v_exp_f32_e32 v190, v203
	v_pk_add_f32 v[160:161], v[160:161], v[178:179]
	v_pk_add_f32 v[166:167], v[166:167], v[184:185]
	v_pk_add_f32 v[178:179], v[214:215], v[218:219]
	v_cvt_pk_bf16_f32 v146, v151, v189
	v_pk_add_f32 v[166:167], v[166:167], v[178:179]
	v_pk_add_f32 v[178:179], v[226:227], v[190:191]
	v_pk_add_f32 v[160:161], v[160:161], v[166:167]
	v_pk_add_f32 v[166:167], v[224:225], v[176:177]
	v_pk_add_f32 v[106:107], v[106:107], v[160:161]
	v_pk_add_f32 v[160:161], v[148:149], v[174:175]
	v_cvt_pk_bf16_f32 v147, v227, v191
	v_pk_add_f32 v[160:161], v[160:161], v[166:167]
	v_pk_add_f32 v[166:167], v[150:151], v[188:189]
	v_pk_add_f32 v[166:167], v[166:167], v[178:179]
	v_cvt_pk_bf16_f32 v150, v150, v188
	v_pk_add_f32 v[160:161], v[160:161], v[166:167]
	v_cvt_pk_bf16_f32 v151, v226, v190
	v_pk_add_f32 v[106:107], v[106:107], v[160:161]
	v_exp_f32_e32 v161, v204
	v_exp_f32_e32 v167, v208
	v_exp_f32_e32 v179, v205
	v_exp_f32_e32 v185, v209
	v_exp_f32_e32 v189, v206
	v_exp_f32_e32 v191, v210
	v_exp_f32_e32 v197, v207
	v_exp_f32_e32 v199, v211
	v_exp_f32_e32 v160, v136
	v_exp_f32_e32 v166, v140
	v_exp_f32_e32 v178, v137
	v_exp_f32_e32 v184, v141
	v_exp_f32_e32 v188, v138
	v_exp_f32_e32 v190, v142
	v_exp_f32_e32 v196, v139
	v_exp_f32_e32 v198, v143
	v_pk_add_f32 v[116:117], v[116:117], v[220:221]
	v_pk_add_f32 v[118:119], v[118:119], v[222:223]
	v_pk_add_f32 v[108:109], v[108:109], v[112:113]
	v_pk_add_f32 v[110:111], v[110:111], v[114:115]
	v_pk_add_f32 v[116:117], v[116:117], v[118:119]
	v_pk_add_f32 v[108:109], v[108:109], v[110:111]
	v_pk_add_f32 v[110:111], v[188:189], v[196:197]
	v_pk_add_f32 v[108:109], v[116:117], v[108:109]
	v_pk_add_f32 v[112:113], v[190:191], v[198:199]
	v_pk_add_f32 v[104:105], v[104:105], v[108:109]
	v_pk_add_f32 v[108:109], v[160:161], v[178:179]
	v_cvt_pk_bf16_f32 v144, v149, v175
	v_pk_add_f32 v[108:109], v[108:109], v[110:111]
	v_pk_add_f32 v[110:111], v[166:167], v[184:185]
	v_cvt_pk_bf16_f32 v145, v225, v177
	v_pk_add_f32 v[110:111], v[110:111], v[112:113]
	v_cvt_pk_bf16_f32 v148, v148, v174
	v_pk_add_f32 v[108:109], v[108:109], v[110:111]
	v_cvt_pk_bf16_f32 v149, v224, v176
	v_pk_add_f32 v[104:105], v[104:105], v[108:109]
	v_cvt_pk_bf16_f32 v174, v161, v179
	v_cvt_pk_bf16_f32 v175, v189, v197
	v_cvt_pk_bf16_f32 v176, v167, v185
	v_cvt_pk_bf16_f32 v177, v191, v199
	v_cvt_pk_bf16_f32 v108, v160, v178
	v_cvt_pk_bf16_f32 v109, v188, v196
	v_cvt_pk_bf16_f32 v110, v166, v184
	v_cvt_pk_bf16_f32 v111, v190, v198
	s_setprio 1
	s_waitcnt lgkmcnt(3)
	v_mfma_f32_16x16x32_bf16 v[94:97], v[98:101], v[144:147], v[94:97]
	s_waitcnt lgkmcnt(2)
	v_mfma_f32_16x16x32_bf16 v[90:93], v[152:155], v[144:147], v[90:93]
	s_waitcnt lgkmcnt(1)
	v_mfma_f32_16x16x32_bf16 v[86:89], v[156:159], v[144:147], v[86:89]
	s_waitcnt lgkmcnt(0)
	v_mfma_f32_16x16x32_bf16 v[82:85], v[170:173], v[144:147], v[82:85]
	v_mfma_f32_16x16x32_bf16 v[78:81], v[98:101], v[148:151], v[78:81]
	v_mfma_f32_16x16x32_bf16 v[74:77], v[152:155], v[148:151], v[74:77]
	v_mfma_f32_16x16x32_bf16 v[70:73], v[156:159], v[148:151], v[70:73]
	v_mfma_f32_16x16x32_bf16 v[66:69], v[170:173], v[148:151], v[66:69]
	v_mfma_f32_16x16x32_bf16 v[62:65], v[98:101], v[174:177], v[62:65]
	v_mfma_f32_16x16x32_bf16 v[58:61], v[152:155], v[174:177], v[58:61]
	v_mfma_f32_16x16x32_bf16 v[54:57], v[156:159], v[174:177], v[54:57]
	v_mfma_f32_16x16x32_bf16 v[50:53], v[170:173], v[174:177], v[50:53]
	v_mfma_f32_16x16x32_bf16 v[38:41], v[98:101], v[108:111], v[38:41]
	v_mfma_f32_16x16x32_bf16 v[34:37], v[152:155], v[108:111], v[34:37]
	v_mfma_f32_16x16x32_bf16 v[30:33], v[156:159], v[108:111], v[30:33]
	v_mfma_f32_16x16x32_bf16 v[26:29], v[170:173], v[108:111], v[26:29]
	s_setprio 0
	s_add_i32 s17, s17, 1
	s_add_i32 s39, s39, 64
	s_cmp_eq_u32 s37, s17
	s_cbranch_scc1 .LBB0_240
